# compact straight-line proj epilogues for sigmoid and silu column tiles; no tile-head vmcnt0
# speedup vs baseline: 1.0104x; 1.0104x over previous
; template <class Epi>
; __device__ __forceinline__ void gemm_phase(LAS unsigned char* lds, const Gemm g, const StaticOrder& S, const Epi& E, const int tidx) {
;     ...
;         const bool has_next = S.next(ui + 1, nxt);
;         const char* nA = has_next ? (const char*)g.A + (size_t)nxt.pm * tstep : cA; const char* nB = has_next ? (const char*)g.Bt + (size_t)nxt.pn * tstep : cB;
;         for (int t = 0; t < nt; t += 2) {
;             const bool last = (t == nt - 2);
;             const char* a1 = cA + (size_t)(t + 1) * kstep;
;             const char* a2 = last ? nA : cA + (size_t)(t + 2) * kstep; const char* b2 = last ? nB : cB + (size_t)(t + 2) * kstep;
;     ...
; #pragma unroll
;         for (int a = 0; a < 2; ++a)
; #pragma unroll
;             for (int b = 0; b < 2; ++b)
; #pragma unroll
;                 for (int m = 0; m < 4; ++m)
; #pragma unroll
;                     for (int n = 0; n < 2; ++n) acc[a][b][m][n] = (f32x4){0.f, 0.f, 0.f, 0.f};
;         cur = nxt; cA = nA; cB = nB; ++ui;
.LBB0_70:
	v_mov_b64_e32 v[0:1], s[2:3]
	s_ashr_i32 s7, s6, 31
	v_cmp_lt_i64_e32 vcc, s[8:9], v[0:1]
	s_lshl_b64 s[0:1], s[6:7], 19
	v_readlane_b32 s8, v253, 6
	v_readlane_b32 s9, v253, 7
	s_add_u32 s8, s8, s0
	s_addc_u32 s9, s9, s1
	s_and_b64 s[0:1], vcc, exec
	s_cselect_b32 s0, s9, s15
	s_cselect_b32 s1, s8, s14
	s_ashr_i32 s5, s4, 31
	s_lshl_b64 s[10:11], s[4:5], 19
	s_add_u32 s10, s25, s10
	s_addc_u32 s11, s26, s11
	s_and_b64 s[18:19], vcc, exec
	s_cselect_b32 s5, s11, s17
	s_cselect_b32 s7, s10, s16
	s_add_u32 s14, s14, 0x40080
	s_addc_u32 s15, s15, 0
	s_add_u32 s22, s16, 0x100
	v_mov_b32_e32 v0, 0
	s_addc_u32 s23, s17, 0
	s_mov_b32 s33, -2
	v_mov_b32_e32 v1, v0
	v_mov_b32_e32 v2, v0
	v_mov_b32_e32 v3, v0
	v_mov_b32_e32 v4, v0
	v_mov_b32_e32 v5, v0
	v_mov_b32_e32 v6, v0
	v_mov_b32_e32 v7, v0
	v_mov_b32_e32 v12, v0
	v_mov_b32_e32 v13, v0
	v_mov_b32_e32 v14, v0
	v_mov_b32_e32 v15, v0
	v_mov_b32_e32 v20, v0
	v_mov_b32_e32 v21, v0
	v_mov_b32_e32 v22, v0
	v_mov_b32_e32 v23, v0
	v_mov_b32_e32 v28, v0
	v_mov_b32_e32 v29, v0
	v_mov_b32_e32 v30, v0
	v_mov_b32_e32 v31, v0
	v_mov_b32_e32 v36, v0
	v_mov_b32_e32 v37, v0
	v_mov_b32_e32 v38, v0
	v_mov_b32_e32 v39, v0
	v_mov_b32_e32 v44, v0
	v_mov_b32_e32 v45, v0
	v_mov_b32_e32 v46, v0
	v_mov_b32_e32 v47, v0
	v_mov_b32_e32 v52, v0
	v_mov_b32_e32 v53, v0
	v_mov_b32_e32 v54, v0
	v_mov_b32_e32 v55, v0
	v_mov_b32_e32 v8, v0
	v_mov_b32_e32 v9, v0
	v_mov_b32_e32 v10, v0
	v_mov_b32_e32 v11, v0
	v_mov_b32_e32 v16, v0
	v_mov_b32_e32 v17, v0
	v_mov_b32_e32 v18, v0
	v_mov_b32_e32 v19, v0
	v_mov_b32_e32 v24, v0
	v_mov_b32_e32 v25, v0
	v_mov_b32_e32 v26, v0
	v_mov_b32_e32 v27, v0
	v_mov_b32_e32 v32, v0
	v_mov_b32_e32 v33, v0
	v_mov_b32_e32 v34, v0
	v_mov_b32_e32 v35, v0
	v_mov_b32_e32 v40, v0
	v_mov_b32_e32 v41, v0
	v_mov_b32_e32 v42, v0
	v_mov_b32_e32 v43, v0
	v_mov_b32_e32 v48, v0
	v_mov_b32_e32 v49, v0
	v_mov_b32_e32 v50, v0
	v_mov_b32_e32 v51, v0
	v_mov_b32_e32 v56, v0
	v_mov_b32_e32 v57, v0
	v_mov_b32_e32 v58, v0
	v_mov_b32_e32 v59, v0
	v_mov_b32_e32 v60, v0
	v_mov_b32_e32 v61, v0
	v_mov_b32_e32 v62, v0
	v_mov_b32_e32 v63, v0
	v_mov_b32_e32 v64, v0
	v_mov_b32_e32 v65, v0
	v_mov_b32_e32 v66, v0
	v_mov_b32_e32 v67, v0
	v_mov_b32_e32 v68, v0
	v_mov_b32_e32 v69, v0
	v_mov_b32_e32 v70, v0
	v_mov_b32_e32 v71, v0
	v_mov_b32_e32 v72, v0
	v_mov_b32_e32 v73, v0
	v_mov_b32_e32 v74, v0
	v_mov_b32_e32 v75, v0
	v_mov_b32_e32 v80, v0
	v_mov_b32_e32 v81, v0
	v_mov_b32_e32 v82, v0
	v_mov_b32_e32 v83, v0
	v_mov_b32_e32 v92, v0
	v_mov_b32_e32 v93, v0
	v_mov_b32_e32 v94, v0
	v_mov_b32_e32 v95, v0
	v_mov_b32_e32 v100, v0
	v_mov_b32_e32 v101, v0
	v_mov_b32_e32 v102, v0
	v_mov_b32_e32 v103, v0
	v_mov_b32_e32 v112, v0
	v_mov_b32_e32 v113, v0
	v_mov_b32_e32 v114, v0
	v_mov_b32_e32 v115, v0
	v_mov_b32_e32 v116, v0
	v_mov_b32_e32 v117, v0
	v_mov_b32_e32 v118, v0
	v_mov_b32_e32 v119, v0
	v_mov_b32_e32 v76, v0
	v_mov_b32_e32 v77, v0
	v_mov_b32_e32 v78, v0
	v_mov_b32_e32 v79, v0
	v_mov_b32_e32 v84, v0
	v_mov_b32_e32 v85, v0
	v_mov_b32_e32 v86, v0
	v_mov_b32_e32 v87, v0
	v_mov_b32_e32 v88, v0
	v_mov_b32_e32 v89, v0
	v_mov_b32_e32 v90, v0
	v_mov_b32_e32 v91, v0
	v_mov_b32_e32 v96, v0
	v_mov_b32_e32 v97, v0
	v_mov_b32_e32 v98, v0
	v_mov_b32_e32 v99, v0
	v_mov_b32_e32 v104, v0
	v_mov_b32_e32 v105, v0
	v_mov_b32_e32 v106, v0
	v_mov_b32_e32 v107, v0
	v_mov_b32_e32 v108, v0
	v_mov_b32_e32 v109, v0
	v_mov_b32_e32 v110, v0
	v_mov_b32_e32 v111, v0
	v_mov_b32_e32 v120, v0
	v_mov_b32_e32 v121, v0
	v_mov_b32_e32 v122, v0
	v_mov_b32_e32 v123, v0
	v_mov_b32_e32 v124, v0
	v_mov_b32_e32 v125, v0
	v_mov_b32_e32 v126, v0
	v_mov_b32_e32 v127, v0
	s_mov_b64 s[44:45], 0x80

; template <class Epi>
; __device__ __forceinline__ void gemm_phase(LAS unsigned char* lds, const Gemm g, const StaticOrder& S, const Epi& E, const int tidx) {
;     ...
;         const bool has_next = S.next(ui + 1, nxt);
;         const char* nA = has_next ? (const char*)g.A + (size_t)nxt.pm * tstep : cA; const char* nB = has_next ? (const char*)g.Bt + (size_t)nxt.pn * tstep : cB;
;         for (int t = 0; t < nt; t += 2) {
;             const bool last = (t == nt - 2);
;             const char* a1 = cA + (size_t)(t + 1) * kstep;
;             const char* a2 = last ? nA : cA + (size_t)(t + 2) * kstep; const char* b2 = last ? nB : cB + (size_t)(t + 2) * kstep;
;     ...
; #pragma unroll
;         for (int a = 0; a < 2; ++a)
; #pragma unroll
;             for (int b = 0; b < 2; ++b)
; #pragma unroll
;                 for (int m = 0; m < 4; ++m)
; #pragma unroll
;                     for (int n = 0; n < 2; ++n) acc[a][b][m][n] = (f32x4){0.f, 0.f, 0.f, 0.f};
;         cur = nxt; cA = nA; cB = nB; ++ui;
.LBB0_712:
	s_add_u32 s2, s8, 0x80
	s_addc_u32 s3, s9, 0
	s_add_u32 s0, s6, 0x100
	v_mov_b32_e32 v8, 0
	s_addc_u32 s1, s7, 0
	s_mov_b32 s4, 0
	v_mov_b32_e32 v9, v8
	v_mov_b32_e32 v10, v8
	v_mov_b32_e32 v11, v8
	v_mov_b32_e32 v12, v8
	v_mov_b32_e32 v13, v8
	v_mov_b32_e32 v14, v8
	v_mov_b32_e32 v15, v8
	v_mov_b32_e32 v24, v8
	v_mov_b32_e32 v25, v8
	v_mov_b32_e32 v26, v8
	v_mov_b32_e32 v27, v8
	v_mov_b32_e32 v28, v8
	v_mov_b32_e32 v29, v8
	v_mov_b32_e32 v30, v8
	v_mov_b32_e32 v31, v8
	v_mov_b32_e32 v40, v8
	v_mov_b32_e32 v41, v8
	v_mov_b32_e32 v42, v8
	v_mov_b32_e32 v43, v8
	v_mov_b32_e32 v44, v8
	v_mov_b32_e32 v45, v8
	v_mov_b32_e32 v46, v8
	v_mov_b32_e32 v47, v8
	v_mov_b32_e32 v56, v8
	v_mov_b32_e32 v57, v8
	v_mov_b32_e32 v58, v8
	v_mov_b32_e32 v59, v8
	v_mov_b32_e32 v60, v8
	v_mov_b32_e32 v61, v8
	v_mov_b32_e32 v62, v8
	v_mov_b32_e32 v63, v8
	v_mov_b32_e32 v0, v8
	v_mov_b32_e32 v1, v8
	v_mov_b32_e32 v2, v8
	v_mov_b32_e32 v3, v8
	v_mov_b32_e32 v4, v8
	v_mov_b32_e32 v5, v8
	v_mov_b32_e32 v6, v8
	v_mov_b32_e32 v7, v8
	v_mov_b32_e32 v16, v8
	v_mov_b32_e32 v17, v8
	v_mov_b32_e32 v18, v8
	v_mov_b32_e32 v19, v8
	v_mov_b32_e32 v20, v8
	v_mov_b32_e32 v21, v8
	v_mov_b32_e32 v22, v8
	v_mov_b32_e32 v23, v8
	v_mov_b32_e32 v32, v8
	v_mov_b32_e32 v33, v8
	v_mov_b32_e32 v34, v8
	v_mov_b32_e32 v35, v8
	v_mov_b32_e32 v36, v8
	v_mov_b32_e32 v37, v8
	v_mov_b32_e32 v38, v8
	v_mov_b32_e32 v39, v8
	v_mov_b32_e32 v48, v8
	v_mov_b32_e32 v49, v8
	v_mov_b32_e32 v50, v8
	v_mov_b32_e32 v51, v8
	v_mov_b32_e32 v52, v8
	v_mov_b32_e32 v53, v8
	v_mov_b32_e32 v54, v8
	v_mov_b32_e32 v55, v8
	v_mov_b32_e32 v72, v8
	v_mov_b32_e32 v73, v8
	v_mov_b32_e32 v74, v8
	v_mov_b32_e32 v75, v8
	v_mov_b32_e32 v76, v8
	v_mov_b32_e32 v77, v8
	v_mov_b32_e32 v78, v8
	v_mov_b32_e32 v79, v8
	v_mov_b32_e32 v88, v8
	v_mov_b32_e32 v89, v8
	v_mov_b32_e32 v90, v8
	v_mov_b32_e32 v91, v8
	v_mov_b32_e32 v92, v8
	v_mov_b32_e32 v93, v8
	v_mov_b32_e32 v94, v8
	v_mov_b32_e32 v95, v8
	v_mov_b32_e32 v104, v8
	v_mov_b32_e32 v105, v8
	v_mov_b32_e32 v106, v8
	v_mov_b32_e32 v107, v8
	v_mov_b32_e32 v108, v8
	v_mov_b32_e32 v109, v8
	v_mov_b32_e32 v110, v8
	v_mov_b32_e32 v111, v8
	v_mov_b32_e32 v120, v8
	v_mov_b32_e32 v121, v8
	v_mov_b32_e32 v122, v8
	v_mov_b32_e32 v123, v8
	v_mov_b32_e32 v124, v8
	v_mov_b32_e32 v125, v8
	v_mov_b32_e32 v126, v8
	v_mov_b32_e32 v127, v8
	v_mov_b32_e32 v64, v8
	v_mov_b32_e32 v65, v8
	v_mov_b32_e32 v66, v8
	v_mov_b32_e32 v67, v8
	v_mov_b32_e32 v68, v8
	v_mov_b32_e32 v69, v8
	v_mov_b32_e32 v70, v8
	v_mov_b32_e32 v71, v8
	v_mov_b32_e32 v80, v8
	v_mov_b32_e32 v81, v8
	v_mov_b32_e32 v82, v8
	v_mov_b32_e32 v83, v8
	v_mov_b32_e32 v84, v8
	v_mov_b32_e32 v85, v8
	v_mov_b32_e32 v86, v8
	v_mov_b32_e32 v87, v8
	v_mov_b32_e32 v96, v8
	v_mov_b32_e32 v97, v8
	v_mov_b32_e32 v98, v8
	v_mov_b32_e32 v99, v8
	v_mov_b32_e32 v100, v8
	v_mov_b32_e32 v101, v8
	v_mov_b32_e32 v102, v8
	v_mov_b32_e32 v103, v8
	v_mov_b32_e32 v112, v8
	v_mov_b32_e32 v113, v8
	v_mov_b32_e32 v114, v8
	v_mov_b32_e32 v115, v8
	v_mov_b32_e32 v116, v8
	v_mov_b32_e32 v117, v8
	v_mov_b32_e32 v118, v8
	v_mov_b32_e32 v119, v8
	s_mov_b64 s[14:15], s[62:63]
	s_mov_b64 s[16:17], 0x80

; __device__ __forceinline__ unsigned cvt_pk_bf16(float lo, float hi) { const f32x2 v = {lo, hi}; const bf16v2_t b = __builtin_convertvector(v, bf16v2_t); return __builtin_bit_cast(unsigned, b); }
; __device__ __forceinline__ float sigmoidf_(float x) { return __builtin_amdgcn_rcpf(1.0f + __builtin_amdgcn_exp2f(x * -1.44269504089f)); }
; __device__ __forceinline__ float siluf_(float x) { return x * __builtin_amdgcn_rcpf(1.0f + __builtin_amdgcn_exp2f(x * -1.44269504089f)); }
;     __device__ __forceinline__ void epi_proj(const f32x4 (&acc)[2][2][4][2], const pg8::Unit& u, int wr, int wc, int fr, int fq) const {
;     ...
;             for (int m = 0; m < 4; ++m) rstd8[ai][m] = rs[row0 + ai * 128 + m * 16];
; #pragma unroll
;         for (int ai = 0; ai < 2; ++ai)
; #pragma unroll
;             for (int m = 0; m < 4; ++m) rstd8[ai][m] = rsqrtf(rstd8[ai][m] * (1.0f / 1024.0f) + EPS);
;     ...
;                         const int slot = u.pn >> 2;
;                         bf16_t* rowp = act + (size_t)slot * SLOT_EL + (size_t)r * 1024 + (colt & 1023);
; #pragma unroll
;                         for (int bj = 0; bj < 2; ++bj) {
;                             f32x4 v0 = acc[ai][bj][m][0] * rstd, v1 = acc[ai][bj][m][1] * rstd;
;                             if (slot < 2) {
;                                 f32x2 a = gelu_pk((f32x2){v0[0], v0[1]}), b = gelu_pk((f32x2){v0[2], v0[3]}), c = gelu_pk((f32x2){v1[0], v1[1]}), d = gelu_pk((f32x2){v1[2], v1[3]});
;                                 v0 = (f32x4){a.x, a.y, b.x, b.y}; v1 = (f32x4){c.x, c.y, d.x, d.y};
;                             } else if (slot == 5) {
; #pragma unroll
;                                 for (int j = 0; j < 4; ++j) { v0[j] = siluf_(v0[j]); v1[j] = siluf_(v1[j]); }
;                             } else if (slot >= 6) {
; #pragma unroll
;                                 for (int j = 0; j < 4; ++j) { v0[j] = sigmoidf_(v0[j]); v1[j] = sigmoidf_(v1[j]); }
;                             }
;                             u32x4 w; w.x = cvt_pk_bf16(v0[0], v0[1]); w.y = cvt_pk_bf16(v0[2], v0[3]); w.z = cvt_pk_bf16(v1[0], v1[1]); w.w = cvt_pk_bf16(v1[2], v1[3]);
;                             *(u32x4*)(rowp + bj * 128) = w;
.Lepi_sig:
	v_readlane_b32 s6, v254, 34
	v_readlane_b32 s7, v254, 35
	s_mov_b64 s[0:1], s[6:7]
	s_load_dwordx2 s[4:5], s[0:1], 0xb0
	s_mov_b64 s[0:1], s[6:7]
	s_mov_b64 s[0:1], s[6:7]
	s_mov_b64 s[0:1], s[6:7]
	s_mov_b64 s[0:1], s[6:7]
	v_lshl_add_u32 v136, s13, 8, v239
	v_ashrrev_i32_e32 v137, 31, v136
	s_mov_b64 s[0:1], s[6:7]
	s_waitcnt lgkmcnt(0)
	v_lshl_add_u64 v[128:129], v[136:137], 2, s[66:67]
	global_load_dword v130, v[128:129], off
	global_load_dword v131, v[128:129], off offset:64
	global_load_dword v132, v[128:129], off offset:128
	global_load_dword v133, v[128:129], off offset:192
	global_load_dword v134, v[128:129], off offset:512
	global_load_dword v135, v[128:129], off offset:576
	global_load_dword v139, v[128:129], off offset:640
	s_nop 0
	global_load_dword v128, v[128:129], off offset:704
	s_mov_b32 s0, 0x800000
	v_lshl_or_b32 v152, s88, 8, v245
	v_and_b32_e32 v152, 0x3ff, v152
	v_ashrrev_i32_e32 v153, 31, v152
	v_lshl_add_u64 v[152:153], v[152:153], 1, s[4:5]
	v_or_b32_e32 v146, 16, v136
	v_or_b32_e32 v142, 32, v136
	v_or_b32_e32 v140, 48, v136
	v_lshlrev_b64 v[136:137], 11, v[136:137]
	v_ashrrev_i32_e32 v147, 31, v146
	v_lshlrev_b64 v[146:147], 11, v[146:147]
	v_ashrrev_i32_e32 v143, 31, v142
	v_lshlrev_b64 v[142:143], 11, v[142:143]
	v_ashrrev_i32_e32 v141, 31, v140
	v_lshlrev_b64 v[140:141], 11, v[140:141]
	s_waitcnt vmcnt(0)
	v_fmamk_f32 v129, v130, 0x3a800000, v237
	v_cmp_gt_f32_e32 vcc, s0, v129
	v_mul_f32_e32 v130, 0x4b800000, v129
	v_fmamk_f32 v128, v128, 0x3a800000, v237
	v_cndmask_b32_e32 v129, v129, v130, vcc
	v_rsq_f32_e32 v129, v129
	s_nop 0
	v_mul_f32_e32 v130, 0x45800000, v129
	v_cndmask_b32_e32 v150, v129, v130, vcc
	v_fmamk_f32 v129, v131, 0x3a800000, v237
	v_cmp_gt_f32_e32 vcc, s0, v129
	v_mul_f32_e32 v130, 0x4b800000, v129
	v_pk_mul_f32 v[154:155], v[118:119], v[150:151] op_sel_hi:[1,0]
	v_cndmask_b32_e32 v129, v129, v130, vcc
	v_rsq_f32_e32 v129, v129
	v_pk_mul_f32 v[156:157], v[116:117], v[150:151] op_sel_hi:[1,0]
	v_pk_mul_f32 v[158:159], v[114:115], v[150:151] op_sel_hi:[1,0]
	v_pk_mul_f32 v[160:161], v[112:113], v[150:151] op_sel_hi:[1,0]
	v_mul_f32_e32 v130, 0x45800000, v129
	v_cndmask_b32_e32 v148, v129, v130, vcc
	v_fmamk_f32 v129, v132, 0x3a800000, v237
	v_cmp_gt_f32_e32 vcc, s0, v129
	v_mul_f32_e32 v130, 0x4b800000, v129
	v_mul_f32_e32 v156, 0xbfb8aa3b, v156
	v_exp_f32_e32 v156, v156
	v_cndmask_b32_e32 v129, v129, v130, vcc
	v_rsq_f32_e32 v129, v129
	v_mul_f32_e32 v160, 0xbfb8aa3b, v160
	v_exp_f32_e32 v160, v160
	v_mul_f32_e32 v157, 0xbfb8aa3b, v157
	v_exp_f32_e32 v157, v157
	v_mul_f32_e32 v161, 0xbfb8aa3b, v161
	v_exp_f32_e32 v161, v161
	v_mul_f32_e32 v130, 0x45800000, v129
	v_cndmask_b32_e32 v144, v129, v130, vcc
	v_fmamk_f32 v129, v133, 0x3a800000, v237
	v_cmp_gt_f32_e32 vcc, s0, v129
	v_mul_f32_e32 v130, 0x4b800000, v129
	v_mul_f32_e32 v154, 0xbfb8aa3b, v154
	v_exp_f32_e32 v154, v154
	v_cndmask_b32_e32 v129, v129, v130, vcc
	v_rsq_f32_e32 v129, v129
	v_mul_f32_e32 v158, 0xbfb8aa3b, v158
	v_exp_f32_e32 v158, v158
	v_mul_f32_e32 v155, 0xbfb8aa3b, v155
	v_exp_f32_e32 v155, v155
	v_mul_f32_e32 v159, 0xbfb8aa3b, v159
	v_exp_f32_e32 v159, v159
	v_mul_f32_e32 v130, 0x45800000, v129
	v_cndmask_b32_e32 v138, v129, v130, vcc
	v_fmamk_f32 v129, v134, 0x3a800000, v237
	v_cmp_gt_f32_e32 vcc, s0, v129
	v_mul_f32_e32 v130, 0x4b800000, v129
	s_nop 0
	v_add_f32_e32 v156, 1.0, v156
	v_add_f32_e32 v157, 1.0, v157
	v_rcp_f32_e32 v156, v156
	v_rcp_f32_e32 v157, v157
	s_nop 0
	v_cndmask_b32_e32 v129, v129, v130, vcc
	v_rsq_f32_e32 v129, v129
	s_nop 0
	v_add_f32_e32 v160, 1.0, v160
	v_add_f32_e32 v161, 1.0, v161
	v_rcp_f32_e32 v160, v160
	v_rcp_f32_e32 v161, v161
	s_nop 0
	s_nop 0
	v_add_f32_e32 v162, 1.0, v154
	v_add_f32_e32 v163, 1.0, v155
	v_rcp_f32_e32 v162, v162
	v_rcp_f32_e32 v163, v163
	s_nop 0
	s_nop 0
	v_add_f32_e32 v158, 1.0, v158
	v_add_f32_e32 v159, 1.0, v159
	v_rcp_f32_e32 v158, v158
	v_rcp_f32_e32 v159, v159
	s_nop 0
	v_mul_f32_e32 v130, 0x45800000, v129
	v_cndmask_b32_e32 v134, v129, v130, vcc
	v_fmamk_f32 v129, v135, 0x3a800000, v237
	v_cmp_gt_f32_e32 vcc, s0, v129
	v_mul_f32_e32 v130, 0x4b800000, v129
	v_cvt_pk_bf16_f32 v154, v156, v157
	v_cndmask_b32_e32 v129, v129, v130, vcc
	v_rsq_f32_e32 v129, v129
	v_cvt_pk_bf16_f32 v155, v162, v163
	v_cvt_pk_bf16_f32 v156, v160, v161
	v_cvt_pk_bf16_f32 v157, v158, v159
	v_mul_f32_e32 v130, 0x45800000, v129
	v_cndmask_b32_e32 v132, v129, v130, vcc
	v_fmamk_f32 v129, v139, 0x3a800000, v237
	v_cmp_gt_f32_e32 vcc, s0, v129
	v_mul_f32_e32 v130, 0x4b800000, v129
	v_pk_mul_f32 v[158:159], v[122:123], v[150:151] op_sel_hi:[1,0]
	v_cndmask_b32_e32 v129, v129, v130, vcc
	v_rsq_f32_e32 v129, v129
	v_mul_f32_e32 v158, 0xbfb8aa3b, v158
	v_exp_f32_e32 v158, v158
	v_mul_f32_e32 v159, 0xbfb8aa3b, v159
	v_exp_f32_e32 v159, v159
	s_nop 0
	v_add_f32_e32 v158, 1.0, v158
	v_add_f32_e32 v159, 1.0, v159
	v_rcp_f32_e32 v158, v158
	v_rcp_f32_e32 v159, v159
	s_nop 0
	v_mul_f32_e32 v130, 0x45800000, v129
	v_cndmask_b32_e32 v130, v129, v130, vcc
	v_cmp_gt_f32_e32 vcc, s0, v128
	s_lshr_b32 s0, s88, 2
	s_mul_i32 s0, s0, 0x4080000
	s_add_u32 s0, s0, 0x8d80000
	s_mov_b32 s1, 0
	v_lshl_add_u64 v[152:153], v[152:153], 0, s[0:1]
	v_lshl_add_u64 v[136:137], v[152:153], 0, v[136:137]
	global_store_dwordx4 v[136:137], v[154:157], off
	v_mul_f32_e32 v129, 0x4b800000, v128
	v_cndmask_b32_e32 v128, v128, v129, vcc
	v_pk_mul_f32 v[154:155], v[126:127], v[150:151] op_sel_hi:[1,0]
	v_pk_mul_f32 v[156:157], v[124:125], v[150:151] op_sel_hi:[1,0]
	v_pk_mul_f32 v[150:151], v[120:121], v[150:151] op_sel_hi:[1,0]
	v_mul_f32_e32 v156, 0xbfb8aa3b, v156
	v_exp_f32_e32 v156, v156
	v_mul_f32_e32 v150, 0xbfb8aa3b, v150
; __device__ __forceinline__ unsigned cvt_pk_bf16(float lo, float hi) { const f32x2 v = {lo, hi}; const bf16v2_t b = __builtin_convertvector(v, bf16v2_t); return __builtin_bit_cast(unsigned, b); }
; __device__ __forceinline__ float sigmoidf_(float x) { return __builtin_amdgcn_rcpf(1.0f + __builtin_amdgcn_exp2f(x * -1.44269504089f)); }
; __device__ __forceinline__ float siluf_(float x) { return x * __builtin_amdgcn_rcpf(1.0f + __builtin_amdgcn_exp2f(x * -1.44269504089f)); }
;     __device__ __forceinline__ void epi_proj(const f32x4 (&acc)[2][2][4][2], const pg8::Unit& u, int wr, int wc, int fr, int fq) const {
;     ...
;                         const int slot = u.pn >> 2;
;                         bf16_t* rowp = act + (size_t)slot * SLOT_EL + (size_t)r * 1024 + (colt & 1023);
; #pragma unroll
;                         for (int bj = 0; bj < 2; ++bj) {
;                             f32x4 v0 = acc[ai][bj][m][0] * rstd, v1 = acc[ai][bj][m][1] * rstd;
;                             if (slot < 2) {
;                                 f32x2 a = gelu_pk((f32x2){v0[0], v0[1]}), b = gelu_pk((f32x2){v0[2], v0[3]}), c = gelu_pk((f32x2){v1[0], v1[1]}), d = gelu_pk((f32x2){v1[2], v1[3]});
;                                 v0 = (f32x4){a.x, a.y, b.x, b.y}; v1 = (f32x4){c.x, c.y, d.x, d.y};
;                             } else if (slot == 5) {
; #pragma unroll
;                                 for (int j = 0; j < 4; ++j) { v0[j] = siluf_(v0[j]); v1[j] = siluf_(v1[j]); }
;                             } else if (slot >= 6) {
; #pragma unroll
;                                 for (int j = 0; j < 4; ++j) { v0[j] = sigmoidf_(v0[j]); v1[j] = sigmoidf_(v1[j]); }
;                             }
;                             u32x4 w; w.x = cvt_pk_bf16(v0[0], v0[1]); w.y = cvt_pk_bf16(v0[2], v0[3]); w.z = cvt_pk_bf16(v1[0], v1[1]); w.w = cvt_pk_bf16(v1[2], v1[3]);
;                             *(u32x4*)(rowp + bj * 128) = w;
	v_exp_f32_e32 v150, v150
	v_mul_f32_e32 v157, 0xbfb8aa3b, v157
	v_exp_f32_e32 v157, v157
	v_mul_f32_e32 v151, 0xbfb8aa3b, v151
	v_exp_f32_e32 v151, v151
	v_mul_f32_e32 v154, 0xbfb8aa3b, v154
	v_exp_f32_e32 v154, v154
	v_mul_f32_e32 v155, 0xbfb8aa3b, v155
	v_exp_f32_e32 v155, v155
	s_nop 0
	v_add_f32_e32 v156, 1.0, v156
	v_add_f32_e32 v157, 1.0, v157
	v_rcp_f32_e32 v156, v156
	v_rcp_f32_e32 v157, v157
	s_nop 0
	s_nop 0
	v_add_f32_e32 v150, 1.0, v150
	v_add_f32_e32 v151, 1.0, v151
	v_rcp_f32_e32 v150, v150
	v_rcp_f32_e32 v151, v151
	s_nop 0
	s_nop 0
	v_add_f32_e32 v160, 1.0, v154
	v_add_f32_e32 v161, 1.0, v155
	v_rcp_f32_e32 v160, v160
	v_rcp_f32_e32 v161, v161
	s_nop 0
	v_cvt_pk_bf16_f32 v154, v156, v157
	v_cvt_pk_bf16_f32 v155, v160, v161
	v_cvt_pk_bf16_f32 v156, v150, v151
	v_cvt_pk_bf16_f32 v157, v158, v159
	global_store_dwordx4 v[136:137], v[154:157], off offset:256
	v_lshl_add_u64 v[150:151], v[152:153], 0, v[146:147]
	v_pk_mul_f32 v[146:147], v[102:103], v[148:149] op_sel_hi:[1,0]
	v_pk_mul_f32 v[154:155], v[100:101], v[148:149] op_sel_hi:[1,0]
	v_pk_mul_f32 v[156:157], v[98:99], v[148:149] op_sel_hi:[1,0]
	v_pk_mul_f32 v[158:159], v[96:97], v[148:149] op_sel_hi:[1,0]
	v_mul_f32_e32 v154, 0xbfb8aa3b, v154
	v_exp_f32_e32 v154, v154
	v_mul_f32_e32 v158, 0xbfb8aa3b, v158
	v_exp_f32_e32 v158, v158
	v_mul_f32_e32 v155, 0xbfb8aa3b, v155
	v_exp_f32_e32 v155, v155
	v_mul_f32_e32 v159, 0xbfb8aa3b, v159
	v_exp_f32_e32 v159, v159
	v_mul_f32_e32 v146, 0xbfb8aa3b, v146
	v_exp_f32_e32 v146, v146
	v_mul_f32_e32 v156, 0xbfb8aa3b, v156
	v_exp_f32_e32 v156, v156
	v_mul_f32_e32 v147, 0xbfb8aa3b, v147
	v_exp_f32_e32 v147, v147
	v_mul_f32_e32 v157, 0xbfb8aa3b, v157
	v_exp_f32_e32 v157, v157
	s_nop 0
	v_add_f32_e32 v154, 1.0, v154
	v_add_f32_e32 v155, 1.0, v155
	v_rcp_f32_e32 v154, v154
	v_rcp_f32_e32 v155, v155
	s_nop 0
	s_nop 0
	v_add_f32_e32 v158, 1.0, v158
	v_add_f32_e32 v159, 1.0, v159
	v_rcp_f32_e32 v158, v158
	v_rcp_f32_e32 v159, v159
	s_nop 0
	s_nop 0
	v_add_f32_e32 v146, 1.0, v146
	v_add_f32_e32 v147, 1.0, v147
	v_rcp_f32_e32 v146, v146
	v_rcp_f32_e32 v147, v147
	s_nop 0
	s_nop 0
	v_add_f32_e32 v160, 1.0, v156
	v_add_f32_e32 v161, 1.0, v157
	v_rcp_f32_e32 v160, v160
	v_rcp_f32_e32 v161, v161
	s_nop 0
	v_cvt_pk_bf16_f32 v154, v154, v155
	v_cvt_pk_bf16_f32 v155, v146, v147
	v_cvt_pk_bf16_f32 v156, v158, v159
	v_cvt_pk_bf16_f32 v157, v160, v161
	global_store_dwordx4 v[150:151], v[154:157], off
	v_pk_mul_f32 v[146:147], v[110:111], v[148:149] op_sel_hi:[1,0]
	v_rsq_f32_e32 v128, v128
	v_pk_mul_f32 v[154:155], v[108:109], v[148:149] op_sel_hi:[1,0]
	v_pk_mul_f32 v[156:157], v[106:107], v[148:149] op_sel_hi:[1,0]
	v_pk_mul_f32 v[148:149], v[104:105], v[148:149] op_sel_hi:[1,0]
	v_mul_f32_e32 v154, 0xbfb8aa3b, v154
	v_exp_f32_e32 v154, v154
	v_mul_f32_e32 v148, 0xbfb8aa3b, v148
	v_exp_f32_e32 v148, v148
	v_mul_f32_e32 v155, 0xbfb8aa3b, v155
	v_exp_f32_e32 v155, v155
	v_mul_f32_e32 v149, 0xbfb8aa3b, v149
	v_exp_f32_e32 v149, v149
	v_mul_f32_e32 v146, 0xbfb8aa3b, v146
	v_exp_f32_e32 v146, v146
	v_mul_f32_e32 v156, 0xbfb8aa3b, v156
	v_exp_f32_e32 v156, v156
	v_mul_f32_e32 v147, 0xbfb8aa3b, v147
	v_exp_f32_e32 v147, v147
	v_mul_f32_e32 v157, 0xbfb8aa3b, v157
	v_exp_f32_e32 v157, v157
	s_nop 0
	v_add_f32_e32 v154, 1.0, v154
	v_add_f32_e32 v155, 1.0, v155
	v_rcp_f32_e32 v154, v154
	v_rcp_f32_e32 v155, v155
	s_nop 0
	s_nop 0
	v_add_f32_e32 v148, 1.0, v148
	v_add_f32_e32 v149, 1.0, v149
	v_rcp_f32_e32 v148, v148
	v_rcp_f32_e32 v149, v149
	s_nop 0
	s_nop 0
	v_add_f32_e32 v158, 1.0, v146
	v_add_f32_e32 v159, 1.0, v147
	v_rcp_f32_e32 v158, v158
	v_rcp_f32_e32 v159, v159
	s_nop 0
	s_nop 0
	v_add_f32_e32 v156, 1.0, v156
	v_add_f32_e32 v157, 1.0, v157
	v_rcp_f32_e32 v156, v156
	v_rcp_f32_e32 v157, v157
	s_nop 0
	v_cvt_pk_bf16_f32 v146, v154, v155
	v_cvt_pk_bf16_f32 v147, v158, v159
	v_cvt_pk_bf16_f32 v148, v148, v149
	v_cvt_pk_bf16_f32 v149, v156, v157
	global_store_dwordx4 v[150:151], v[146:149], off offset:256
	v_lshl_add_u64 v[150:151], v[152:153], 0, v[142:143]
	v_pk_mul_f32 v[142:143], v[86:87], v[144:145] op_sel_hi:[1,0]
	v_pk_mul_f32 v[146:147], v[84:85], v[144:145] op_sel_hi:[1,0]
	v_pk_mul_f32 v[148:149], v[82:83], v[144:145] op_sel_hi:[1,0]
	v_pk_mul_f32 v[154:155], v[80:81], v[144:145] op_sel_hi:[1,0]
	v_mul_f32_e32 v146, 0xbfb8aa3b, v146
	v_exp_f32_e32 v146, v146
	v_mul_f32_e32 v154, 0xbfb8aa3b, v154
	v_exp_f32_e32 v154, v154
	v_mul_f32_e32 v147, 0xbfb8aa3b, v147
	v_exp_f32_e32 v147, v147
	v_mul_f32_e32 v155, 0xbfb8aa3b, v155
	v_exp_f32_e32 v155, v155
	v_mul_f32_e32 v142, 0xbfb8aa3b, v142
	v_exp_f32_e32 v142, v142
	v_mul_f32_e32 v148, 0xbfb8aa3b, v148
	v_exp_f32_e32 v148, v148
	v_mul_f32_e32 v143, 0xbfb8aa3b, v143
	v_exp_f32_e32 v143, v143
	v_mul_f32_e32 v149, 0xbfb8aa3b, v149
	v_exp_f32_e32 v149, v149
	s_nop 0
	v_add_f32_e32 v146, 1.0, v146
	v_add_f32_e32 v147, 1.0, v147
	v_rcp_f32_e32 v146, v146
	v_rcp_f32_e32 v147, v147
	s_nop 0
	s_nop 0
	v_add_f32_e32 v154, 1.0, v154
	v_add_f32_e32 v155, 1.0, v155
	v_rcp_f32_e32 v154, v154
	v_rcp_f32_e32 v155, v155
	s_nop 0
	s_nop 0
	v_add_f32_e32 v142, 1.0, v142
	v_add_f32_e32 v143, 1.0, v143
	v_rcp_f32_e32 v142, v142
	v_rcp_f32_e32 v143, v143
	s_nop 0
	s_nop 0
	v_add_f32_e32 v156, 1.0, v148
	v_add_f32_e32 v157, 1.0, v149
	v_rcp_f32_e32 v156, v156
	v_rcp_f32_e32 v157, v157
	s_nop 0
	v_cvt_pk_bf16_f32 v146, v146, v147
	v_cvt_pk_bf16_f32 v147, v142, v143
	v_cvt_pk_bf16_f32 v148, v154, v155
	v_cvt_pk_bf16_f32 v149, v156, v157
	global_store_dwordx4 v[150:151], v[146:149], off
	v_pk_mul_f32 v[142:143], v[94:95], v[144:145] op_sel_hi:[1,0]
	s_mov_b64 s[0:1], 0x40000
	v_pk_mul_f32 v[146:147], v[92:93], v[144:145] op_sel_hi:[1,0]
; __device__ __forceinline__ unsigned cvt_pk_bf16(float lo, float hi) { const f32x2 v = {lo, hi}; const bf16v2_t b = __builtin_convertvector(v, bf16v2_t); return __builtin_bit_cast(unsigned, b); }
; __device__ __forceinline__ float sigmoidf_(float x) { return __builtin_amdgcn_rcpf(1.0f + __builtin_amdgcn_exp2f(x * -1.44269504089f)); }
; __device__ __forceinline__ float siluf_(float x) { return x * __builtin_amdgcn_rcpf(1.0f + __builtin_amdgcn_exp2f(x * -1.44269504089f)); }
;     __device__ __forceinline__ void epi_proj(const f32x4 (&acc)[2][2][4][2], const pg8::Unit& u, int wr, int wc, int fr, int fq) const {
;     ...
;                         const int slot = u.pn >> 2;
;                         bf16_t* rowp = act + (size_t)slot * SLOT_EL + (size_t)r * 1024 + (colt & 1023);
; #pragma unroll
;                         for (int bj = 0; bj < 2; ++bj) {
;                             f32x4 v0 = acc[ai][bj][m][0] * rstd, v1 = acc[ai][bj][m][1] * rstd;
;                             if (slot < 2) {
;                                 f32x2 a = gelu_pk((f32x2){v0[0], v0[1]}), b = gelu_pk((f32x2){v0[2], v0[3]}), c = gelu_pk((f32x2){v1[0], v1[1]}), d = gelu_pk((f32x2){v1[2], v1[3]});
;                                 v0 = (f32x4){a.x, a.y, b.x, b.y}; v1 = (f32x4){c.x, c.y, d.x, d.y};
;                             } else if (slot == 5) {
; #pragma unroll
;                                 for (int j = 0; j < 4; ++j) { v0[j] = siluf_(v0[j]); v1[j] = siluf_(v1[j]); }
;                             } else if (slot >= 6) {
; #pragma unroll
;                                 for (int j = 0; j < 4; ++j) { v0[j] = sigmoidf_(v0[j]); v1[j] = sigmoidf_(v1[j]); }
;                             }
;                             u32x4 w; w.x = cvt_pk_bf16(v0[0], v0[1]); w.y = cvt_pk_bf16(v0[2], v0[3]); w.z = cvt_pk_bf16(v1[0], v1[1]); w.w = cvt_pk_bf16(v1[2], v1[3]);
;                             *(u32x4*)(rowp + bj * 128) = w;
	v_pk_mul_f32 v[148:149], v[90:91], v[144:145] op_sel_hi:[1,0]
	v_pk_mul_f32 v[144:145], v[88:89], v[144:145] op_sel_hi:[1,0]
	v_mul_f32_e32 v146, 0xbfb8aa3b, v146
	v_exp_f32_e32 v146, v146
	v_mul_f32_e32 v144, 0xbfb8aa3b, v144
	v_exp_f32_e32 v144, v144
	v_mul_f32_e32 v147, 0xbfb8aa3b, v147
	v_exp_f32_e32 v147, v147
	v_mul_f32_e32 v145, 0xbfb8aa3b, v145
	v_exp_f32_e32 v145, v145
	v_mul_f32_e32 v142, 0xbfb8aa3b, v142
	v_exp_f32_e32 v142, v142
	v_mul_f32_e32 v148, 0xbfb8aa3b, v148
	v_exp_f32_e32 v148, v148
	v_mul_f32_e32 v143, 0xbfb8aa3b, v143
	v_exp_f32_e32 v143, v143
	v_mul_f32_e32 v149, 0xbfb8aa3b, v149
	v_exp_f32_e32 v149, v149
	s_nop 0
	v_add_f32_e32 v146, 1.0, v146
	v_add_f32_e32 v147, 1.0, v147
	v_rcp_f32_e32 v146, v146
	v_rcp_f32_e32 v147, v147
	s_nop 0
	s_nop 0
	v_add_f32_e32 v144, 1.0, v144
	v_add_f32_e32 v145, 1.0, v145
	v_rcp_f32_e32 v144, v144
	v_rcp_f32_e32 v145, v145
	s_nop 0
	s_nop 0
	v_add_f32_e32 v154, 1.0, v142
	v_add_f32_e32 v155, 1.0, v143
	v_rcp_f32_e32 v154, v154
	v_rcp_f32_e32 v155, v155
	s_nop 0
	s_nop 0
	v_add_f32_e32 v148, 1.0, v148
	v_add_f32_e32 v149, 1.0, v149
	v_rcp_f32_e32 v148, v148
	v_rcp_f32_e32 v149, v149
	s_nop 0
	v_cvt_pk_bf16_f32 v142, v146, v147
	v_cvt_pk_bf16_f32 v143, v154, v155
	v_cvt_pk_bf16_f32 v144, v144, v145
	v_cvt_pk_bf16_f32 v145, v148, v149
	global_store_dwordx4 v[150:151], v[142:145], off offset:256
	v_pk_mul_f32 v[146:147], v[66:67], v[138:139] op_sel_hi:[1,0]
	v_pk_mul_f32 v[148:149], v[64:65], v[138:139] op_sel_hi:[1,0]
	v_lshl_add_u64 v[144:145], v[152:153], 0, v[140:141]
	v_pk_mul_f32 v[140:141], v[70:71], v[138:139] op_sel_hi:[1,0]
	v_pk_mul_f32 v[142:143], v[68:69], v[138:139] op_sel_hi:[1,0]
	v_mul_f32_e32 v148, 0xbfb8aa3b, v148
	v_exp_f32_e32 v148, v148
	v_mul_f32_e32 v142, 0xbfb8aa3b, v142
	v_exp_f32_e32 v142, v142
	v_mul_f32_e32 v143, 0xbfb8aa3b, v143
	v_exp_f32_e32 v143, v143
	v_mul_f32_e32 v149, 0xbfb8aa3b, v149
	v_exp_f32_e32 v149, v149
	v_mul_f32_e32 v140, 0xbfb8aa3b, v140
	v_exp_f32_e32 v140, v140
	v_mul_f32_e32 v146, 0xbfb8aa3b, v146
	v_exp_f32_e32 v146, v146
	v_mul_f32_e32 v141, 0xbfb8aa3b, v141
	v_exp_f32_e32 v141, v141
	v_mul_f32_e32 v147, 0xbfb8aa3b, v147
	v_exp_f32_e32 v147, v147
	s_nop 0
	v_add_f32_e32 v142, 1.0, v142
	v_add_f32_e32 v143, 1.0, v143
	v_rcp_f32_e32 v142, v142
	v_rcp_f32_e32 v143, v143
	s_nop 0
	s_nop 0
	v_add_f32_e32 v148, 1.0, v148
	v_add_f32_e32 v149, 1.0, v149
	v_rcp_f32_e32 v148, v148
	v_rcp_f32_e32 v149, v149
	s_nop 0
	s_nop 0
	v_add_f32_e32 v150, 1.0, v140
	v_add_f32_e32 v151, 1.0, v141
	v_rcp_f32_e32 v150, v150
	v_rcp_f32_e32 v151, v151
	s_nop 0
	s_nop 0
	v_add_f32_e32 v146, 1.0, v146
	v_add_f32_e32 v147, 1.0, v147
	v_rcp_f32_e32 v146, v146
	v_rcp_f32_e32 v147, v147
	s_nop 0
	v_cvt_pk_bf16_f32 v140, v142, v143
	v_cvt_pk_bf16_f32 v141, v150, v151
	v_cvt_pk_bf16_f32 v142, v148, v149
	v_cvt_pk_bf16_f32 v143, v146, v147
	global_store_dwordx4 v[144:145], v[140:143], off
	v_pk_mul_f32 v[146:147], v[74:75], v[138:139] op_sel_hi:[1,0]
	v_mul_f32_e32 v129, 0x45800000, v128
	v_pk_mul_f32 v[140:141], v[78:79], v[138:139] op_sel_hi:[1,0]
	v_pk_mul_f32 v[142:143], v[76:77], v[138:139] op_sel_hi:[1,0]
	v_pk_mul_f32 v[138:139], v[72:73], v[138:139] op_sel_hi:[1,0]
	v_mul_f32_e32 v142, 0xbfb8aa3b, v142
	v_exp_f32_e32 v142, v142
	v_mul_f32_e32 v138, 0xbfb8aa3b, v138
	v_exp_f32_e32 v138, v138
	v_mul_f32_e32 v139, 0xbfb8aa3b, v139
	v_exp_f32_e32 v139, v139
	v_mul_f32_e32 v143, 0xbfb8aa3b, v143
	v_exp_f32_e32 v143, v143
	s_nop 0
	v_add_f32_e32 v148, 1.0, v138
	v_add_f32_e32 v149, 1.0, v139
	v_rcp_f32_e32 v148, v148
	v_rcp_f32_e32 v149, v149
	s_nop 0
	v_mul_f32_e32 v138, 0xbfb8aa3b, v140
	v_exp_f32_e32 v138, v138
	v_mul_f32_e32 v140, 0xbfb8aa3b, v146
	v_exp_f32_e32 v140, v140
	v_mul_f32_e32 v139, 0xbfb8aa3b, v141
	v_exp_f32_e32 v139, v139
	v_mul_f32_e32 v141, 0xbfb8aa3b, v147
	v_exp_f32_e32 v141, v141
	s_nop 0
	v_add_f32_e32 v142, 1.0, v142
	v_add_f32_e32 v143, 1.0, v143
	v_rcp_f32_e32 v142, v142
	v_rcp_f32_e32 v143, v143
	s_nop 0
	s_nop 0
	v_add_f32_e32 v150, 1.0, v138
	v_add_f32_e32 v151, 1.0, v139
	v_rcp_f32_e32 v150, v150
	v_rcp_f32_e32 v151, v151
	s_nop 0
	s_nop 0
	v_add_f32_e32 v146, 1.0, v140
	v_add_f32_e32 v147, 1.0, v141
	v_rcp_f32_e32 v146, v146
	v_rcp_f32_e32 v147, v147
	s_nop 0
	v_cvt_pk_bf16_f32 v138, v142, v143
	v_cvt_pk_bf16_f32 v139, v150, v151
	v_cvt_pk_bf16_f32 v140, v148, v149
	v_cvt_pk_bf16_f32 v141, v146, v147
	global_store_dwordx4 v[144:145], v[138:141], off offset:256
	v_pk_mul_f32 v[144:145], v[50:51], v[134:135] op_sel_hi:[1,0]
	v_pk_mul_f32 v[146:147], v[48:49], v[134:135] op_sel_hi:[1,0]
	v_pk_mul_f32 v[140:141], v[52:53], v[134:135] op_sel_hi:[1,0]
	v_pk_mul_f32 v[138:139], v[54:55], v[134:135] op_sel_hi:[1,0]
	v_mul_f32_e32 v140, 0xbfb8aa3b, v140
	v_exp_f32_e32 v140, v140
	v_mul_f32_e32 v141, 0xbfb8aa3b, v141
	v_exp_f32_e32 v141, v141
	v_mul_f32_e32 v144, 0xbfb8aa3b, v144
	v_exp_f32_e32 v144, v144
	v_mul_f32_e32 v145, 0xbfb8aa3b, v145
	v_exp_f32_e32 v145, v145
	v_lshl_add_u64 v[142:143], v[136:137], 0, s[0:1]
	v_mul_f32_e32 v146, 0xbfb8aa3b, v146
	v_exp_f32_e32 v146, v146
	s_nop 0
	v_add_f32_e32 v140, 1.0, v140
	v_add_f32_e32 v141, 1.0, v141
	v_rcp_f32_e32 v140, v140
	v_rcp_f32_e32 v141, v141
	s_nop 0
	v_mul_f32_e32 v147, 0xbfb8aa3b, v147
	v_exp_f32_e32 v147, v147
	v_mul_f32_e32 v138, 0xbfb8aa3b, v138
	v_exp_f32_e32 v138, v138
	v_mul_f32_e32 v139, 0xbfb8aa3b, v139
	v_exp_f32_e32 v139, v139
	s_nop 0
	v_add_f32_e32 v144, 1.0, v144
	v_add_f32_e32 v145, 1.0, v145
	v_rcp_f32_e32 v144, v144
	v_rcp_f32_e32 v145, v145
	s_nop 0
	s_mov_b32 s0, 0x40000
	v_cndmask_b32_e32 v128, v128, v129, vcc
	s_nop 0
	v_add_f32_e32 v146, 1.0, v146
; __device__ __forceinline__ unsigned cvt_pk_bf16(float lo, float hi) { const f32x2 v = {lo, hi}; const bf16v2_t b = __builtin_convertvector(v, bf16v2_t); return __builtin_bit_cast(unsigned, b); }
; __device__ __forceinline__ float sigmoidf_(float x) { return __builtin_amdgcn_rcpf(1.0f + __builtin_amdgcn_exp2f(x * -1.44269504089f)); }
; __device__ __forceinline__ float siluf_(float x) { return x * __builtin_amdgcn_rcpf(1.0f + __builtin_amdgcn_exp2f(x * -1.44269504089f)); }
;     __device__ __forceinline__ void epi_proj(const f32x4 (&acc)[2][2][4][2], const pg8::Unit& u, int wr, int wc, int fr, int fq) const {
;     ...
;                         const int slot = u.pn >> 2;
;                         bf16_t* rowp = act + (size_t)slot * SLOT_EL + (size_t)r * 1024 + (colt & 1023);
; #pragma unroll
;                         for (int bj = 0; bj < 2; ++bj) {
;                             f32x4 v0 = acc[ai][bj][m][0] * rstd, v1 = acc[ai][bj][m][1] * rstd;
;                             if (slot < 2) {
;                                 f32x2 a = gelu_pk((f32x2){v0[0], v0[1]}), b = gelu_pk((f32x2){v0[2], v0[3]}), c = gelu_pk((f32x2){v1[0], v1[1]}), d = gelu_pk((f32x2){v1[2], v1[3]});
;                                 v0 = (f32x4){a.x, a.y, b.x, b.y}; v1 = (f32x4){c.x, c.y, d.x, d.y};
;                             } else if (slot == 5) {
; #pragma unroll
;                                 for (int j = 0; j < 4; ++j) { v0[j] = siluf_(v0[j]); v1[j] = siluf_(v1[j]); }
;                             } else if (slot >= 6) {
; #pragma unroll
;                                 for (int j = 0; j < 4; ++j) { v0[j] = sigmoidf_(v0[j]); v1[j] = sigmoidf_(v1[j]); }
;                             }
;                             u32x4 w; w.x = cvt_pk_bf16(v0[0], v0[1]); w.y = cvt_pk_bf16(v0[2], v0[3]); w.z = cvt_pk_bf16(v1[0], v1[1]); w.w = cvt_pk_bf16(v1[2], v1[3]);
;                             *(u32x4*)(rowp + bj * 128) = w;
	v_add_f32_e32 v147, 1.0, v147
	v_rcp_f32_e32 v146, v146
	v_rcp_f32_e32 v147, v147
	s_nop 0
	s_nop 0
	v_add_f32_e32 v148, 1.0, v138
	v_add_f32_e32 v149, 1.0, v139
	v_rcp_f32_e32 v148, v148
	v_rcp_f32_e32 v149, v149
	s_nop 0
	v_cvt_pk_bf16_f32 v138, v140, v141
	v_cvt_pk_bf16_f32 v141, v144, v145
	v_add_co_u32_e32 v144, vcc, s0, v136
	v_cvt_pk_bf16_f32 v139, v148, v149
	v_cvt_pk_bf16_f32 v140, v146, v147
	v_addc_co_u32_e32 v145, vcc, 0, v137, vcc
	global_store_dwordx4 v[144:145], v[138:141], off
	v_pk_mul_f32 v[144:145], v[58:59], v[134:135] op_sel_hi:[1,0]
	s_mov_b64 s[0:1], 0x48000
	v_pk_mul_f32 v[138:139], v[62:63], v[134:135] op_sel_hi:[1,0]
	v_pk_mul_f32 v[140:141], v[60:61], v[134:135] op_sel_hi:[1,0]
	v_pk_mul_f32 v[134:135], v[56:57], v[134:135] op_sel_hi:[1,0]
	v_mul_f32_e32 v140, 0xbfb8aa3b, v140
	v_exp_f32_e32 v140, v140
	v_mul_f32_e32 v134, 0xbfb8aa3b, v134
	v_exp_f32_e32 v134, v134
	v_mul_f32_e32 v141, 0xbfb8aa3b, v141
	v_exp_f32_e32 v141, v141
	v_mul_f32_e32 v135, 0xbfb8aa3b, v135
	v_exp_f32_e32 v135, v135
	v_mul_f32_e32 v138, 0xbfb8aa3b, v138
	v_exp_f32_e32 v138, v138
	v_mul_f32_e32 v144, 0xbfb8aa3b, v144
	v_exp_f32_e32 v144, v144
	v_mul_f32_e32 v139, 0xbfb8aa3b, v139
	v_exp_f32_e32 v139, v139
	v_mul_f32_e32 v145, 0xbfb8aa3b, v145
	v_exp_f32_e32 v145, v145
	s_nop 0
	v_add_f32_e32 v140, 1.0, v140
	v_add_f32_e32 v141, 1.0, v141
	v_rcp_f32_e32 v140, v140
	v_rcp_f32_e32 v141, v141
	s_nop 0
	s_nop 0
	v_add_f32_e32 v134, 1.0, v134
	v_add_f32_e32 v135, 1.0, v135
	v_rcp_f32_e32 v134, v134
	v_rcp_f32_e32 v135, v135
	s_nop 0
	s_nop 0
	v_add_f32_e32 v146, 1.0, v138
	v_add_f32_e32 v147, 1.0, v139
	v_rcp_f32_e32 v146, v146
	v_rcp_f32_e32 v147, v147
	s_nop 0
	s_nop 0
	v_add_f32_e32 v144, 1.0, v144
	v_add_f32_e32 v145, 1.0, v145
	v_rcp_f32_e32 v144, v144
	v_rcp_f32_e32 v145, v145
	s_nop 0
	v_cvt_pk_bf16_f32 v138, v140, v141
	v_cvt_pk_bf16_f32 v139, v146, v147
	v_cvt_pk_bf16_f32 v140, v134, v135
	v_cvt_pk_bf16_f32 v141, v144, v145
	global_store_dwordx4 v[142:143], v[138:141], off offset:256
	v_pk_mul_f32 v[134:135], v[38:39], v[132:133] op_sel_hi:[1,0]
	v_pk_mul_f32 v[144:145], v[32:33], v[132:133] op_sel_hi:[1,0]
	v_pk_mul_f32 v[138:139], v[36:37], v[132:133] op_sel_hi:[1,0]
	v_pk_mul_f32 v[140:141], v[34:35], v[132:133] op_sel_hi:[1,0]
	v_mul_f32_e32 v138, 0xbfb8aa3b, v138
	v_exp_f32_e32 v138, v138
	v_mul_f32_e32 v139, 0xbfb8aa3b, v139
	v_exp_f32_e32 v139, v139
	v_mul_f32_e32 v134, 0xbfb8aa3b, v134
	v_exp_f32_e32 v134, v134
	v_mul_f32_e32 v135, 0xbfb8aa3b, v135
	v_exp_f32_e32 v135, v135
	v_lshl_add_u64 v[142:143], v[136:137], 0, s[0:1]
	v_mul_f32_e32 v144, 0xbfb8aa3b, v144
	v_exp_f32_e32 v144, v144
	s_nop 0
	v_add_f32_e32 v138, 1.0, v138
	v_add_f32_e32 v139, 1.0, v139
	v_rcp_f32_e32 v138, v138
	v_rcp_f32_e32 v139, v139
	s_nop 0
	v_mul_f32_e32 v145, 0xbfb8aa3b, v145
	v_exp_f32_e32 v145, v145
	v_mul_f32_e32 v140, 0xbfb8aa3b, v140
	v_exp_f32_e32 v140, v140
	s_nop 0
	v_add_f32_e32 v134, 1.0, v134
	v_add_f32_e32 v135, 1.0, v135
	v_rcp_f32_e32 v134, v134
	v_rcp_f32_e32 v135, v135
	s_nop 0
	v_mul_f32_e32 v141, 0xbfb8aa3b, v141
	v_exp_f32_e32 v141, v141
	s_mov_b32 s0, 0x48000
	s_nop 0
	v_add_f32_e32 v144, 1.0, v144
	v_add_f32_e32 v145, 1.0, v145
	v_rcp_f32_e32 v144, v144
	v_rcp_f32_e32 v145, v145
	s_nop 0
	s_nop 0
	v_add_f32_e32 v146, 1.0, v140
	v_add_f32_e32 v147, 1.0, v141
	v_rcp_f32_e32 v146, v146
	v_rcp_f32_e32 v147, v147
	s_nop 0
	v_cvt_pk_bf16_f32 v138, v138, v139
	v_cvt_pk_bf16_f32 v139, v134, v135
	v_add_co_u32_e32 v134, vcc, s0, v136
	v_cvt_pk_bf16_f32 v140, v144, v145
	v_cvt_pk_bf16_f32 v141, v146, v147
	v_addc_co_u32_e32 v135, vcc, 0, v137, vcc
	global_store_dwordx4 v[134:135], v[138:141], off
	v_pk_mul_f32 v[134:135], v[46:47], v[132:133] op_sel_hi:[1,0]
	s_mov_b64 s[0:1], 0x50000
	v_pk_mul_f32 v[138:139], v[44:45], v[132:133] op_sel_hi:[1,0]
	v_pk_mul_f32 v[140:141], v[42:43], v[132:133] op_sel_hi:[1,0]
	v_pk_mul_f32 v[132:133], v[40:41], v[132:133] op_sel_hi:[1,0]
	v_mul_f32_e32 v138, 0xbfb8aa3b, v138
	v_exp_f32_e32 v138, v138
	v_mul_f32_e32 v132, 0xbfb8aa3b, v132
	v_exp_f32_e32 v132, v132
	v_mul_f32_e32 v133, 0xbfb8aa3b, v133
	v_exp_f32_e32 v133, v133
	v_mul_f32_e32 v139, 0xbfb8aa3b, v139
	v_exp_f32_e32 v139, v139
	s_nop 0
	v_add_f32_e32 v144, 1.0, v132
	v_add_f32_e32 v145, 1.0, v133
	v_rcp_f32_e32 v144, v144
	v_rcp_f32_e32 v145, v145
	s_nop 0
	v_mul_f32_e32 v132, 0xbfb8aa3b, v134
	v_exp_f32_e32 v132, v132
	v_mul_f32_e32 v134, 0xbfb8aa3b, v140
	v_exp_f32_e32 v134, v134
	v_mul_f32_e32 v133, 0xbfb8aa3b, v135
	v_exp_f32_e32 v133, v133
	v_mul_f32_e32 v135, 0xbfb8aa3b, v141
	v_exp_f32_e32 v135, v135
	s_nop 0
	v_add_f32_e32 v138, 1.0, v138
	v_add_f32_e32 v139, 1.0, v139
	v_rcp_f32_e32 v138, v138
	v_rcp_f32_e32 v139, v139
	s_nop 0
	s_nop 0
	v_add_f32_e32 v146, 1.0, v132
	v_add_f32_e32 v147, 1.0, v133
	v_rcp_f32_e32 v146, v146
	v_rcp_f32_e32 v147, v147
	s_nop 0
	s_nop 0
	v_add_f32_e32 v140, 1.0, v134
	v_add_f32_e32 v141, 1.0, v135
	v_rcp_f32_e32 v140, v140
	v_rcp_f32_e32 v141, v141
	s_nop 0
	v_cvt_pk_bf16_f32 v132, v138, v139
	v_cvt_pk_bf16_f32 v133, v146, v147
	v_cvt_pk_bf16_f32 v134, v144, v145
	v_cvt_pk_bf16_f32 v135, v140, v141
	global_store_dwordx4 v[142:143], v[132:135], off offset:256
	v_pk_mul_f32 v[140:141], v[18:19], v[130:131] op_sel_hi:[1,0]
	v_pk_mul_f32 v[142:143], v[16:17], v[130:131] op_sel_hi:[1,0]
	v_pk_mul_f32 v[134:135], v[20:21], v[130:131] op_sel_hi:[1,0]
	v_pk_mul_f32 v[132:133], v[22:23], v[130:131] op_sel_hi:[1,0]
	v_mul_f32_e32 v134, 0xbfb8aa3b, v134
	v_exp_f32_e32 v134, v134
	v_mul_f32_e32 v135, 0xbfb8aa3b, v135
	v_exp_f32_e32 v135, v135
	v_mul_f32_e32 v140, 0xbfb8aa3b, v140
	v_exp_f32_e32 v140, v140
; __device__ __forceinline__ unsigned cvt_pk_bf16(float lo, float hi) { const f32x2 v = {lo, hi}; const bf16v2_t b = __builtin_convertvector(v, bf16v2_t); return __builtin_bit_cast(unsigned, b); }
; __device__ __forceinline__ float sigmoidf_(float x) { return __builtin_amdgcn_rcpf(1.0f + __builtin_amdgcn_exp2f(x * -1.44269504089f)); }
; __device__ __forceinline__ float siluf_(float x) { return x * __builtin_amdgcn_rcpf(1.0f + __builtin_amdgcn_exp2f(x * -1.44269504089f)); }
;     __device__ __forceinline__ void epi_proj(const f32x4 (&acc)[2][2][4][2], const pg8::Unit& u, int wr, int wc, int fr, int fq) const {
;     ...
;                         const int slot = u.pn >> 2;
;                         bf16_t* rowp = act + (size_t)slot * SLOT_EL + (size_t)r * 1024 + (colt & 1023);
; #pragma unroll
;                         for (int bj = 0; bj < 2; ++bj) {
;                             f32x4 v0 = acc[ai][bj][m][0] * rstd, v1 = acc[ai][bj][m][1] * rstd;
;                             if (slot < 2) {
;                                 f32x2 a = gelu_pk((f32x2){v0[0], v0[1]}), b = gelu_pk((f32x2){v0[2], v0[3]}), c = gelu_pk((f32x2){v1[0], v1[1]}), d = gelu_pk((f32x2){v1[2], v1[3]});
;                                 v0 = (f32x4){a.x, a.y, b.x, b.y}; v1 = (f32x4){c.x, c.y, d.x, d.y};
;                             } else if (slot == 5) {
; #pragma unroll
;                                 for (int j = 0; j < 4; ++j) { v0[j] = siluf_(v0[j]); v1[j] = siluf_(v1[j]); }
;                             } else if (slot >= 6) {
; #pragma unroll
;                                 for (int j = 0; j < 4; ++j) { v0[j] = sigmoidf_(v0[j]); v1[j] = sigmoidf_(v1[j]); }
;                             }
;                             u32x4 w; w.x = cvt_pk_bf16(v0[0], v0[1]); w.y = cvt_pk_bf16(v0[2], v0[3]); w.z = cvt_pk_bf16(v1[0], v1[1]); w.w = cvt_pk_bf16(v1[2], v1[3]);
;                             *(u32x4*)(rowp + bj * 128) = w;
	v_mul_f32_e32 v141, 0xbfb8aa3b, v141
	v_exp_f32_e32 v141, v141
	v_lshl_add_u64 v[138:139], v[136:137], 0, s[0:1]
	v_mul_f32_e32 v142, 0xbfb8aa3b, v142
	v_exp_f32_e32 v142, v142
	s_nop 0
	v_add_f32_e32 v134, 1.0, v134
	v_add_f32_e32 v135, 1.0, v135
	v_rcp_f32_e32 v134, v134
	v_rcp_f32_e32 v135, v135
	s_nop 0
	v_mul_f32_e32 v143, 0xbfb8aa3b, v143
	v_exp_f32_e32 v143, v143
	v_mul_f32_e32 v132, 0xbfb8aa3b, v132
	v_exp_f32_e32 v132, v132
	v_mul_f32_e32 v133, 0xbfb8aa3b, v133
	v_exp_f32_e32 v133, v133
	s_nop 0
	v_add_f32_e32 v140, 1.0, v140
	v_add_f32_e32 v141, 1.0, v141
	v_rcp_f32_e32 v140, v140
	v_rcp_f32_e32 v141, v141
	s_nop 0
	s_mov_b32 s0, 0x50000
	s_nop 0
	v_add_f32_e32 v142, 1.0, v142
	v_add_f32_e32 v143, 1.0, v143
	v_rcp_f32_e32 v142, v142
	v_rcp_f32_e32 v143, v143
	s_nop 0
	s_nop 0
	v_add_f32_e32 v144, 1.0, v132
	v_add_f32_e32 v145, 1.0, v133
	v_rcp_f32_e32 v144, v144
	v_rcp_f32_e32 v145, v145
	s_nop 0
	v_cvt_pk_bf16_f32 v132, v134, v135
	v_cvt_pk_bf16_f32 v135, v140, v141
	v_add_co_u32_e32 v140, vcc, s0, v136
	v_cvt_pk_bf16_f32 v133, v144, v145
	v_cvt_pk_bf16_f32 v134, v142, v143
	v_addc_co_u32_e32 v141, vcc, 0, v137, vcc
	global_store_dwordx4 v[140:141], v[132:135], off
	v_pk_mul_f32 v[140:141], v[26:27], v[130:131] op_sel_hi:[1,0]
	s_mov_b64 s[0:1], 0x58000
	v_pk_mul_f32 v[132:133], v[30:31], v[130:131] op_sel_hi:[1,0]
	v_pk_mul_f32 v[134:135], v[28:29], v[130:131] op_sel_hi:[1,0]
	v_pk_mul_f32 v[130:131], v[24:25], v[130:131] op_sel_hi:[1,0]
	v_mul_f32_e32 v134, 0xbfb8aa3b, v134
	v_exp_f32_e32 v134, v134
	v_mul_f32_e32 v130, 0xbfb8aa3b, v130
	v_exp_f32_e32 v130, v130
	v_mul_f32_e32 v131, 0xbfb8aa3b, v131
	v_exp_f32_e32 v131, v131
	v_mul_f32_e32 v135, 0xbfb8aa3b, v135
	v_exp_f32_e32 v135, v135
	s_nop 0
	v_add_f32_e32 v142, 1.0, v130
	v_add_f32_e32 v143, 1.0, v131
	v_rcp_f32_e32 v142, v142
	v_rcp_f32_e32 v143, v143
	s_nop 0
	v_mul_f32_e32 v130, 0xbfb8aa3b, v132
	v_exp_f32_e32 v130, v130
	v_mul_f32_e32 v132, 0xbfb8aa3b, v140
	v_exp_f32_e32 v132, v132
	v_mul_f32_e32 v131, 0xbfb8aa3b, v133
	v_exp_f32_e32 v131, v131
	v_mul_f32_e32 v133, 0xbfb8aa3b, v141
	v_exp_f32_e32 v133, v133
	s_nop 0
	v_add_f32_e32 v134, 1.0, v134
	v_add_f32_e32 v135, 1.0, v135
	v_rcp_f32_e32 v134, v134
	v_rcp_f32_e32 v135, v135
	s_nop 0
	s_nop 0
	v_add_f32_e32 v144, 1.0, v130
	v_add_f32_e32 v145, 1.0, v131
	v_rcp_f32_e32 v144, v144
	v_rcp_f32_e32 v145, v145
	s_nop 0
	s_nop 0
	v_add_f32_e32 v140, 1.0, v132
	v_add_f32_e32 v141, 1.0, v133
	v_rcp_f32_e32 v140, v140
	v_rcp_f32_e32 v141, v141
	s_nop 0
	v_cvt_pk_bf16_f32 v130, v134, v135
	v_cvt_pk_bf16_f32 v131, v144, v145
	v_cvt_pk_bf16_f32 v132, v142, v143
	v_cvt_pk_bf16_f32 v133, v140, v141
	global_store_dwordx4 v[138:139], v[130:133], off offset:256
	v_pk_mul_f32 v[138:139], v[2:3], v[128:129] op_sel_hi:[1,0]
	v_pk_mul_f32 v[140:141], v[0:1], v[128:129] op_sel_hi:[1,0]
	v_pk_mul_f32 v[130:131], v[6:7], v[128:129] op_sel_hi:[1,0]
	v_pk_mul_f32 v[132:133], v[4:5], v[128:129] op_sel_hi:[1,0]
	v_lshl_add_u64 v[134:135], v[136:137], 0, s[0:1]
	v_mul_f32_e32 v132, 0xbfb8aa3b, v132
	v_exp_f32_e32 v132, v132
	v_mul_f32_e32 v140, 0xbfb8aa3b, v140
	v_exp_f32_e32 v140, v140
	v_mul_f32_e32 v133, 0xbfb8aa3b, v133
	v_exp_f32_e32 v133, v133
	v_mul_f32_e32 v141, 0xbfb8aa3b, v141
	v_exp_f32_e32 v141, v141
	v_mul_f32_e32 v130, 0xbfb8aa3b, v130
	v_exp_f32_e32 v130, v130
	v_mul_f32_e32 v138, 0xbfb8aa3b, v138
	v_exp_f32_e32 v138, v138
	v_mul_f32_e32 v131, 0xbfb8aa3b, v131
	v_exp_f32_e32 v131, v131
	v_mul_f32_e32 v139, 0xbfb8aa3b, v139
	v_exp_f32_e32 v139, v139
	s_mov_b32 s0, 0x58000
	s_nop 0
	v_add_f32_e32 v132, 1.0, v132
	v_add_f32_e32 v133, 1.0, v133
	v_rcp_f32_e32 v132, v132
	v_rcp_f32_e32 v133, v133
	s_nop 0
	s_nop 0
	v_add_f32_e32 v140, 1.0, v140
	v_add_f32_e32 v141, 1.0, v141
	v_rcp_f32_e32 v140, v140
	v_rcp_f32_e32 v141, v141
	s_nop 0
	s_nop 0
	v_add_f32_e32 v142, 1.0, v130
	v_add_f32_e32 v143, 1.0, v131
	v_rcp_f32_e32 v142, v142
	v_rcp_f32_e32 v143, v143
	s_nop 0
	s_nop 0
	v_add_f32_e32 v138, 1.0, v138
	v_add_f32_e32 v139, 1.0, v139
	v_rcp_f32_e32 v138, v138
	v_rcp_f32_e32 v139, v139
	s_nop 0
	v_add_co_u32_e32 v136, vcc, s0, v136
	v_cvt_pk_bf16_f32 v130, v132, v133
	v_cvt_pk_bf16_f32 v131, v142, v143
	v_cvt_pk_bf16_f32 v132, v140, v141
	v_cvt_pk_bf16_f32 v133, v138, v139
	v_addc_co_u32_e32 v137, vcc, 0, v137, vcc
	global_store_dwordx4 v[136:137], v[130:133], off
	v_pk_mul_f32 v[136:137], v[10:11], v[128:129] op_sel_hi:[1,0]
	s_nop 0
	v_pk_mul_f32 v[130:131], v[14:15], v[128:129] op_sel_hi:[1,0]
	v_pk_mul_f32 v[132:133], v[12:13], v[128:129] op_sel_hi:[1,0]
	v_pk_mul_f32 v[128:129], v[8:9], v[128:129] op_sel_hi:[1,0]
	v_mul_f32_e32 v132, 0xbfb8aa3b, v132
	v_exp_f32_e32 v132, v132
	v_mul_f32_e32 v128, 0xbfb8aa3b, v128
	v_exp_f32_e32 v128, v128
	v_mul_f32_e32 v129, 0xbfb8aa3b, v129
	v_exp_f32_e32 v129, v129
	v_mul_f32_e32 v133, 0xbfb8aa3b, v133
	v_exp_f32_e32 v133, v133
	s_nop 0
	v_add_f32_e32 v138, 1.0, v128
	v_add_f32_e32 v139, 1.0, v129
	v_rcp_f32_e32 v138, v138
	v_rcp_f32_e32 v139, v139
	s_nop 0
	v_mul_f32_e32 v128, 0xbfb8aa3b, v130
	v_exp_f32_e32 v128, v128
	v_mul_f32_e32 v130, 0xbfb8aa3b, v136
	v_exp_f32_e32 v130, v130
	v_mul_f32_e32 v129, 0xbfb8aa3b, v131
	v_exp_f32_e32 v129, v129
	v_mul_f32_e32 v131, 0xbfb8aa3b, v137
	v_exp_f32_e32 v131, v131
	s_nop 0
	v_add_f32_e32 v132, 1.0, v132
	v_add_f32_e32 v133, 1.0, v133
	v_rcp_f32_e32 v132, v132
	v_rcp_f32_e32 v133, v133
	s_nop 0
	s_nop 0
	v_add_f32_e32 v140, 1.0, v128
	v_add_f32_e32 v141, 1.0, v129
	v_rcp_f32_e32 v140, v140
	v_rcp_f32_e32 v141, v141
	s_nop 0
	s_nop 0
	v_add_f32_e32 v136, 1.0, v130
	v_add_f32_e32 v137, 1.0, v131
	v_rcp_f32_e32 v136, v136
	v_rcp_f32_e32 v137, v137
	s_nop 0
	v_cvt_pk_bf16_f32 v128, v132, v133
	v_cvt_pk_bf16_f32 v129, v140, v141
	v_cvt_pk_bf16_f32 v130, v138, v139
	v_cvt_pk_bf16_f32 v131, v136, v137
	global_store_dwordx4 v[134:135], v[128:131], off offset:256
	s_branch .LBB0_701
; __device__ __forceinline__ unsigned cvt_pk_bf16(float lo, float hi) { const f32x2 v = {lo, hi}; const bf16v2_t b = __builtin_convertvector(v, bf16v2_t); return __builtin_bit_cast(unsigned, b); }
; __device__ __forceinline__ float sigmoidf_(float x) { return __builtin_amdgcn_rcpf(1.0f + __builtin_amdgcn_exp2f(x * -1.44269504089f)); }
; __device__ __forceinline__ float siluf_(float x) { return x * __builtin_amdgcn_rcpf(1.0f + __builtin_amdgcn_exp2f(x * -1.44269504089f)); }
;     __device__ __forceinline__ void epi_proj(const f32x4 (&acc)[2][2][4][2], const pg8::Unit& u, int wr, int wc, int fr, int fq) const {
;     ...
;             for (int m = 0; m < 4; ++m) rstd8[ai][m] = rs[row0 + ai * 128 + m * 16];
; #pragma unroll
;         for (int ai = 0; ai < 2; ++ai)
; #pragma unroll
;             for (int m = 0; m < 4; ++m) rstd8[ai][m] = rsqrtf(rstd8[ai][m] * (1.0f / 1024.0f) + EPS);
;     ...
;                         const int slot = u.pn >> 2;
;                         bf16_t* rowp = act + (size_t)slot * SLOT_EL + (size_t)r * 1024 + (colt & 1023);
; #pragma unroll
;                         for (int bj = 0; bj < 2; ++bj) {
;                             f32x4 v0 = acc[ai][bj][m][0] * rstd, v1 = acc[ai][bj][m][1] * rstd;
;                             if (slot < 2) {
;                                 f32x2 a = gelu_pk((f32x2){v0[0], v0[1]}), b = gelu_pk((f32x2){v0[2], v0[3]}), c = gelu_pk((f32x2){v1[0], v1[1]}), d = gelu_pk((f32x2){v1[2], v1[3]});
;                                 v0 = (f32x4){a.x, a.y, b.x, b.y}; v1 = (f32x4){c.x, c.y, d.x, d.y};
;                             } else if (slot == 5) {
; #pragma unroll
;                                 for (int j = 0; j < 4; ++j) { v0[j] = siluf_(v0[j]); v1[j] = siluf_(v1[j]); }
;                             } else if (slot >= 6) {
; #pragma unroll
;                                 for (int j = 0; j < 4; ++j) { v0[j] = sigmoidf_(v0[j]); v1[j] = sigmoidf_(v1[j]); }
;                             }
;                             u32x4 w; w.x = cvt_pk_bf16(v0[0], v0[1]); w.y = cvt_pk_bf16(v0[2], v0[3]); w.z = cvt_pk_bf16(v1[0], v1[1]); w.w = cvt_pk_bf16(v1[2], v1[3]);
;                             *(u32x4*)(rowp + bj * 128) = w;
.Lepi_silu:
	v_readlane_b32 s6, v254, 34
	v_readlane_b32 s7, v254, 35
	s_mov_b64 s[0:1], s[6:7]
	s_load_dwordx2 s[4:5], s[0:1], 0xb0
	s_mov_b64 s[0:1], s[6:7]
	s_mov_b64 s[0:1], s[6:7]
	s_mov_b64 s[0:1], s[6:7]
	s_mov_b64 s[0:1], s[6:7]
	v_lshl_add_u32 v136, s13, 8, v239
	v_ashrrev_i32_e32 v137, 31, v136
	s_mov_b64 s[0:1], s[6:7]
	s_waitcnt lgkmcnt(0)
	v_lshl_add_u64 v[128:129], v[136:137], 2, s[66:67]
	global_load_dword v130, v[128:129], off
	global_load_dword v131, v[128:129], off offset:64
	global_load_dword v132, v[128:129], off offset:128
	global_load_dword v133, v[128:129], off offset:192
	global_load_dword v134, v[128:129], off offset:512
	global_load_dword v135, v[128:129], off offset:576
	global_load_dword v139, v[128:129], off offset:640
	s_nop 0
	global_load_dword v128, v[128:129], off offset:704
	s_mov_b32 s0, 0x800000
	v_lshl_or_b32 v152, s88, 8, v245
	v_and_b32_e32 v152, 0x3ff, v152
	v_ashrrev_i32_e32 v153, 31, v152
	v_lshl_add_u64 v[152:153], v[152:153], 1, s[4:5]
	v_or_b32_e32 v146, 16, v136
	v_or_b32_e32 v142, 32, v136
	v_or_b32_e32 v140, 48, v136
	v_lshlrev_b64 v[136:137], 11, v[136:137]
	v_ashrrev_i32_e32 v147, 31, v146
	v_lshlrev_b64 v[146:147], 11, v[146:147]
	v_ashrrev_i32_e32 v143, 31, v142
	v_lshlrev_b64 v[142:143], 11, v[142:143]
	v_ashrrev_i32_e32 v141, 31, v140
	v_lshlrev_b64 v[140:141], 11, v[140:141]
	s_waitcnt vmcnt(0)
	v_fmamk_f32 v129, v130, 0x3a800000, v237
	v_cmp_gt_f32_e32 vcc, s0, v129
	v_mul_f32_e32 v130, 0x4b800000, v129
	v_fmamk_f32 v128, v128, 0x3a800000, v237
	v_cndmask_b32_e32 v129, v129, v130, vcc
	v_rsq_f32_e32 v129, v129
	s_nop 0
	v_mul_f32_e32 v130, 0x45800000, v129
	v_cndmask_b32_e32 v150, v129, v130, vcc
	v_fmamk_f32 v129, v131, 0x3a800000, v237
	v_cmp_gt_f32_e32 vcc, s0, v129
	v_mul_f32_e32 v130, 0x4b800000, v129
	v_pk_mul_f32 v[154:155], v[118:119], v[150:151] op_sel_hi:[1,0]
	v_cndmask_b32_e32 v129, v129, v130, vcc
	v_rsq_f32_e32 v129, v129
	v_pk_mul_f32 v[156:157], v[116:117], v[150:151] op_sel_hi:[1,0]
	v_pk_mul_f32 v[158:159], v[114:115], v[150:151] op_sel_hi:[1,0]
	v_pk_mul_f32 v[160:161], v[112:113], v[150:151] op_sel_hi:[1,0]
	v_mul_f32_e32 v130, 0x45800000, v129
	v_cndmask_b32_e32 v148, v129, v130, vcc
	v_fmamk_f32 v129, v132, 0x3a800000, v237
	v_cmp_gt_f32_e32 vcc, s0, v129
	v_mul_f32_e32 v130, 0x4b800000, v129
	v_mul_f32_e32 v164, 0xbfb8aa3b, v156
	v_exp_f32_e32 v164, v164
	v_cndmask_b32_e32 v129, v129, v130, vcc
	v_rsq_f32_e32 v129, v129
	v_mul_f32_e32 v166, 0xbfb8aa3b, v160
	v_exp_f32_e32 v166, v166
	v_mul_f32_e32 v165, 0xbfb8aa3b, v157
	v_exp_f32_e32 v165, v165
	v_mul_f32_e32 v167, 0xbfb8aa3b, v161
	v_exp_f32_e32 v167, v167
	v_mul_f32_e32 v130, 0x45800000, v129
	v_cndmask_b32_e32 v144, v129, v130, vcc
	v_fmamk_f32 v129, v133, 0x3a800000, v237
	v_cmp_gt_f32_e32 vcc, s0, v129
	v_mul_f32_e32 v130, 0x4b800000, v129
	v_mul_f32_e32 v168, 0xbfb8aa3b, v154
	v_exp_f32_e32 v168, v168
	v_cndmask_b32_e32 v129, v129, v130, vcc
	v_rsq_f32_e32 v129, v129
	v_mul_f32_e32 v170, 0xbfb8aa3b, v158
	v_exp_f32_e32 v170, v170
	v_mul_f32_e32 v169, 0xbfb8aa3b, v155
	v_exp_f32_e32 v169, v169
	v_mul_f32_e32 v171, 0xbfb8aa3b, v159
	v_exp_f32_e32 v171, v171
	v_mul_f32_e32 v130, 0x45800000, v129
	v_cndmask_b32_e32 v138, v129, v130, vcc
	v_fmamk_f32 v129, v134, 0x3a800000, v237
	v_cmp_gt_f32_e32 vcc, s0, v129
	v_mul_f32_e32 v130, 0x4b800000, v129
	s_nop 0
	v_add_f32_e32 v164, 1.0, v164
	v_add_f32_e32 v165, 1.0, v165
	v_rcp_f32_e32 v164, v164
	v_rcp_f32_e32 v165, v165
	s_nop 0
	v_pk_mul_f32 v[156:157], v[156:157], v[164:165]
	v_cndmask_b32_e32 v129, v129, v130, vcc
	v_rsq_f32_e32 v129, v129
	s_nop 0
	v_add_f32_e32 v166, 1.0, v166
	v_add_f32_e32 v167, 1.0, v167
	v_rcp_f32_e32 v166, v166
	v_rcp_f32_e32 v167, v167
	s_nop 0
	v_pk_mul_f32 v[160:161], v[160:161], v[166:167]
	s_nop 0
	v_add_f32_e32 v168, 1.0, v168
	v_add_f32_e32 v169, 1.0, v169
	v_rcp_f32_e32 v168, v168
	v_rcp_f32_e32 v169, v169
	s_nop 0
	v_pk_mul_f32 v[162:163], v[154:155], v[168:169]
	s_nop 0
	v_add_f32_e32 v170, 1.0, v170
	v_add_f32_e32 v171, 1.0, v171
	v_rcp_f32_e32 v170, v170
	v_rcp_f32_e32 v171, v171
	s_nop 0
	v_pk_mul_f32 v[158:159], v[158:159], v[170:171]
	v_mul_f32_e32 v130, 0x45800000, v129
	v_cndmask_b32_e32 v134, v129, v130, vcc
	v_fmamk_f32 v129, v135, 0x3a800000, v237
	v_cmp_gt_f32_e32 vcc, s0, v129
	v_mul_f32_e32 v130, 0x4b800000, v129
	v_cvt_pk_bf16_f32 v154, v156, v157
	v_cndmask_b32_e32 v129, v129, v130, vcc
	v_rsq_f32_e32 v129, v129
	v_cvt_pk_bf16_f32 v155, v162, v163
	v_cvt_pk_bf16_f32 v156, v160, v161
	v_cvt_pk_bf16_f32 v157, v158, v159
	v_mul_f32_e32 v130, 0x45800000, v129
	v_cndmask_b32_e32 v132, v129, v130, vcc
	v_fmamk_f32 v129, v139, 0x3a800000, v237
	v_cmp_gt_f32_e32 vcc, s0, v129
	v_mul_f32_e32 v130, 0x4b800000, v129
	v_pk_mul_f32 v[158:159], v[122:123], v[150:151] op_sel_hi:[1,0]
	v_cndmask_b32_e32 v129, v129, v130, vcc
	v_rsq_f32_e32 v129, v129
	v_mul_f32_e32 v172, 0xbfb8aa3b, v158
	v_exp_f32_e32 v172, v172
	v_mul_f32_e32 v173, 0xbfb8aa3b, v159
	v_exp_f32_e32 v173, v173
	s_nop 0
	v_add_f32_e32 v172, 1.0, v172
	v_add_f32_e32 v173, 1.0, v173
	v_rcp_f32_e32 v172, v172
	v_rcp_f32_e32 v173, v173
	s_nop 0
	v_pk_mul_f32 v[158:159], v[158:159], v[172:173]
	v_mul_f32_e32 v130, 0x45800000, v129
	v_cndmask_b32_e32 v130, v129, v130, vcc
	v_cmp_gt_f32_e32 vcc, s0, v128
	s_lshr_b32 s0, s88, 2
	s_mul_i32 s0, s0, 0x4080000
	s_add_u32 s0, s0, 0x8d80000
	s_mov_b32 s1, 0
	v_lshl_add_u64 v[152:153], v[152:153], 0, s[0:1]
	v_lshl_add_u64 v[136:137], v[152:153], 0, v[136:137]
	global_store_dwordx4 v[136:137], v[154:157], off
	v_mul_f32_e32 v129, 0x4b800000, v128
	v_cndmask_b32_e32 v128, v128, v129, vcc
	v_pk_mul_f32 v[154:155], v[126:127], v[150:151] op_sel_hi:[1,0]
; __device__ __forceinline__ unsigned cvt_pk_bf16(float lo, float hi) { const f32x2 v = {lo, hi}; const bf16v2_t b = __builtin_convertvector(v, bf16v2_t); return __builtin_bit_cast(unsigned, b); }
; __device__ __forceinline__ float sigmoidf_(float x) { return __builtin_amdgcn_rcpf(1.0f + __builtin_amdgcn_exp2f(x * -1.44269504089f)); }
; __device__ __forceinline__ float siluf_(float x) { return x * __builtin_amdgcn_rcpf(1.0f + __builtin_amdgcn_exp2f(x * -1.44269504089f)); }
;     __device__ __forceinline__ void epi_proj(const f32x4 (&acc)[2][2][4][2], const pg8::Unit& u, int wr, int wc, int fr, int fq) const {
;     ...
;                         const int slot = u.pn >> 2;
;                         bf16_t* rowp = act + (size_t)slot * SLOT_EL + (size_t)r * 1024 + (colt & 1023);
; #pragma unroll
;                         for (int bj = 0; bj < 2; ++bj) {
;                             f32x4 v0 = acc[ai][bj][m][0] * rstd, v1 = acc[ai][bj][m][1] * rstd;
;                             if (slot < 2) {
;                                 f32x2 a = gelu_pk((f32x2){v0[0], v0[1]}), b = gelu_pk((f32x2){v0[2], v0[3]}), c = gelu_pk((f32x2){v1[0], v1[1]}), d = gelu_pk((f32x2){v1[2], v1[3]});
;                                 v0 = (f32x4){a.x, a.y, b.x, b.y}; v1 = (f32x4){c.x, c.y, d.x, d.y};
;                             } else if (slot == 5) {
; #pragma unroll
;                                 for (int j = 0; j < 4; ++j) { v0[j] = siluf_(v0[j]); v1[j] = siluf_(v1[j]); }
;                             } else if (slot >= 6) {
; #pragma unroll
;                                 for (int j = 0; j < 4; ++j) { v0[j] = sigmoidf_(v0[j]); v1[j] = sigmoidf_(v1[j]); }
;                             }
;                             u32x4 w; w.x = cvt_pk_bf16(v0[0], v0[1]); w.y = cvt_pk_bf16(v0[2], v0[3]); w.z = cvt_pk_bf16(v1[0], v1[1]); w.w = cvt_pk_bf16(v1[2], v1[3]);
;                             *(u32x4*)(rowp + bj * 128) = w;
	v_pk_mul_f32 v[156:157], v[124:125], v[150:151] op_sel_hi:[1,0]
	v_pk_mul_f32 v[150:151], v[120:121], v[150:151] op_sel_hi:[1,0]
	v_mul_f32_e32 v174, 0xbfb8aa3b, v156
	v_exp_f32_e32 v174, v174
	v_mul_f32_e32 v176, 0xbfb8aa3b, v150
	v_exp_f32_e32 v176, v176
	v_mul_f32_e32 v175, 0xbfb8aa3b, v157
	v_exp_f32_e32 v175, v175
	v_mul_f32_e32 v177, 0xbfb8aa3b, v151
	v_exp_f32_e32 v177, v177
	v_mul_f32_e32 v178, 0xbfb8aa3b, v154
	v_exp_f32_e32 v178, v178
	v_mul_f32_e32 v179, 0xbfb8aa3b, v155
	v_exp_f32_e32 v179, v179
	s_nop 0
	v_add_f32_e32 v174, 1.0, v174
	v_add_f32_e32 v175, 1.0, v175
	v_rcp_f32_e32 v174, v174
	v_rcp_f32_e32 v175, v175
	s_nop 0
	v_pk_mul_f32 v[156:157], v[156:157], v[174:175]
	s_nop 0
	v_add_f32_e32 v176, 1.0, v176
	v_add_f32_e32 v177, 1.0, v177
	v_rcp_f32_e32 v176, v176
	v_rcp_f32_e32 v177, v177
	s_nop 0
	v_pk_mul_f32 v[150:151], v[150:151], v[176:177]
	s_nop 0
	v_add_f32_e32 v178, 1.0, v178
	v_add_f32_e32 v179, 1.0, v179
	v_rcp_f32_e32 v178, v178
	v_rcp_f32_e32 v179, v179
	s_nop 0
	v_pk_mul_f32 v[160:161], v[154:155], v[178:179]
	v_cvt_pk_bf16_f32 v154, v156, v157
	v_cvt_pk_bf16_f32 v155, v160, v161
	v_cvt_pk_bf16_f32 v156, v150, v151
	v_cvt_pk_bf16_f32 v157, v158, v159
	global_store_dwordx4 v[136:137], v[154:157], off offset:256
	v_lshl_add_u64 v[150:151], v[152:153], 0, v[146:147]
	v_pk_mul_f32 v[146:147], v[102:103], v[148:149] op_sel_hi:[1,0]
	v_pk_mul_f32 v[154:155], v[100:101], v[148:149] op_sel_hi:[1,0]
	v_pk_mul_f32 v[156:157], v[98:99], v[148:149] op_sel_hi:[1,0]
	v_pk_mul_f32 v[158:159], v[96:97], v[148:149] op_sel_hi:[1,0]
	v_mul_f32_e32 v180, 0xbfb8aa3b, v154
	v_exp_f32_e32 v180, v180
	v_mul_f32_e32 v182, 0xbfb8aa3b, v158
	v_exp_f32_e32 v182, v182
	v_mul_f32_e32 v181, 0xbfb8aa3b, v155
	v_exp_f32_e32 v181, v181
	v_mul_f32_e32 v183, 0xbfb8aa3b, v159
	v_exp_f32_e32 v183, v183
	v_mul_f32_e32 v184, 0xbfb8aa3b, v146
	v_exp_f32_e32 v184, v184
	v_mul_f32_e32 v186, 0xbfb8aa3b, v156
	v_exp_f32_e32 v186, v186
	v_mul_f32_e32 v185, 0xbfb8aa3b, v147
	v_exp_f32_e32 v185, v185
	v_mul_f32_e32 v187, 0xbfb8aa3b, v157
	v_exp_f32_e32 v187, v187
	s_nop 0
	v_add_f32_e32 v180, 1.0, v180
	v_add_f32_e32 v181, 1.0, v181
	v_rcp_f32_e32 v180, v180
	v_rcp_f32_e32 v181, v181
	s_nop 0
	v_pk_mul_f32 v[154:155], v[154:155], v[180:181]
	s_nop 0
	v_add_f32_e32 v182, 1.0, v182
	v_add_f32_e32 v183, 1.0, v183
	v_rcp_f32_e32 v182, v182
	v_rcp_f32_e32 v183, v183
	s_nop 0
	v_pk_mul_f32 v[158:159], v[158:159], v[182:183]
	s_nop 0
	v_add_f32_e32 v184, 1.0, v184
	v_add_f32_e32 v185, 1.0, v185
	v_rcp_f32_e32 v184, v184
	v_rcp_f32_e32 v185, v185
	s_nop 0
	v_pk_mul_f32 v[146:147], v[146:147], v[184:185]
	s_nop 0
	v_add_f32_e32 v186, 1.0, v186
	v_add_f32_e32 v187, 1.0, v187
	v_rcp_f32_e32 v186, v186
	v_rcp_f32_e32 v187, v187
	s_nop 0
	v_pk_mul_f32 v[160:161], v[156:157], v[186:187]
	v_cvt_pk_bf16_f32 v154, v154, v155
	v_cvt_pk_bf16_f32 v155, v146, v147
	v_cvt_pk_bf16_f32 v156, v158, v159
	v_cvt_pk_bf16_f32 v157, v160, v161
	global_store_dwordx4 v[150:151], v[154:157], off
	v_pk_mul_f32 v[146:147], v[110:111], v[148:149] op_sel_hi:[1,0]
	v_rsq_f32_e32 v128, v128
	v_pk_mul_f32 v[154:155], v[108:109], v[148:149] op_sel_hi:[1,0]
	v_pk_mul_f32 v[156:157], v[106:107], v[148:149] op_sel_hi:[1,0]
	v_pk_mul_f32 v[148:149], v[104:105], v[148:149] op_sel_hi:[1,0]
	v_mul_f32_e32 v188, 0xbfb8aa3b, v154
	v_exp_f32_e32 v188, v188
	v_mul_f32_e32 v190, 0xbfb8aa3b, v148
	v_exp_f32_e32 v190, v190
	v_mul_f32_e32 v189, 0xbfb8aa3b, v155
	v_exp_f32_e32 v189, v189
	v_mul_f32_e32 v191, 0xbfb8aa3b, v149
	v_exp_f32_e32 v191, v191
	v_mul_f32_e32 v164, 0xbfb8aa3b, v146
	v_exp_f32_e32 v164, v164
	v_mul_f32_e32 v166, 0xbfb8aa3b, v156
	v_exp_f32_e32 v166, v166
	v_mul_f32_e32 v165, 0xbfb8aa3b, v147
	v_exp_f32_e32 v165, v165
	v_mul_f32_e32 v167, 0xbfb8aa3b, v157
	v_exp_f32_e32 v167, v167
	s_nop 0
	v_add_f32_e32 v188, 1.0, v188
	v_add_f32_e32 v189, 1.0, v189
	v_rcp_f32_e32 v188, v188
	v_rcp_f32_e32 v189, v189
	s_nop 0
	v_pk_mul_f32 v[154:155], v[154:155], v[188:189]
	s_nop 0
	v_add_f32_e32 v190, 1.0, v190
	v_add_f32_e32 v191, 1.0, v191
	v_rcp_f32_e32 v190, v190
	v_rcp_f32_e32 v191, v191
	s_nop 0
	v_pk_mul_f32 v[148:149], v[148:149], v[190:191]
	s_nop 0
	v_add_f32_e32 v164, 1.0, v164
	v_add_f32_e32 v165, 1.0, v165
	v_rcp_f32_e32 v164, v164
	v_rcp_f32_e32 v165, v165
	s_nop 0
	v_pk_mul_f32 v[158:159], v[146:147], v[164:165]
	s_nop 0
	v_add_f32_e32 v166, 1.0, v166
	v_add_f32_e32 v167, 1.0, v167
	v_rcp_f32_e32 v166, v166
	v_rcp_f32_e32 v167, v167
	s_nop 0
	v_pk_mul_f32 v[156:157], v[156:157], v[166:167]
	v_cvt_pk_bf16_f32 v146, v154, v155
	v_cvt_pk_bf16_f32 v147, v158, v159
	v_cvt_pk_bf16_f32 v148, v148, v149
	v_cvt_pk_bf16_f32 v149, v156, v157
	global_store_dwordx4 v[150:151], v[146:149], off offset:256
	v_lshl_add_u64 v[150:151], v[152:153], 0, v[142:143]
	v_pk_mul_f32 v[142:143], v[86:87], v[144:145] op_sel_hi:[1,0]
	v_pk_mul_f32 v[146:147], v[84:85], v[144:145] op_sel_hi:[1,0]
	v_pk_mul_f32 v[148:149], v[82:83], v[144:145] op_sel_hi:[1,0]
	v_pk_mul_f32 v[154:155], v[80:81], v[144:145] op_sel_hi:[1,0]
	v_mul_f32_e32 v168, 0xbfb8aa3b, v146
	v_exp_f32_e32 v168, v168
	v_mul_f32_e32 v170, 0xbfb8aa3b, v154
	v_exp_f32_e32 v170, v170
	v_mul_f32_e32 v169, 0xbfb8aa3b, v147
	v_exp_f32_e32 v169, v169
	v_mul_f32_e32 v171, 0xbfb8aa3b, v155
	v_exp_f32_e32 v171, v171
	v_mul_f32_e32 v172, 0xbfb8aa3b, v142
	v_exp_f32_e32 v172, v172
	v_mul_f32_e32 v174, 0xbfb8aa3b, v148
	v_exp_f32_e32 v174, v174
	v_mul_f32_e32 v173, 0xbfb8aa3b, v143
	v_exp_f32_e32 v173, v173
	v_mul_f32_e32 v175, 0xbfb8aa3b, v149
	v_exp_f32_e32 v175, v175
	s_nop 0
	v_add_f32_e32 v168, 1.0, v168
	v_add_f32_e32 v169, 1.0, v169
	v_rcp_f32_e32 v168, v168
; __device__ __forceinline__ unsigned cvt_pk_bf16(float lo, float hi) { const f32x2 v = {lo, hi}; const bf16v2_t b = __builtin_convertvector(v, bf16v2_t); return __builtin_bit_cast(unsigned, b); }
; __device__ __forceinline__ float sigmoidf_(float x) { return __builtin_amdgcn_rcpf(1.0f + __builtin_amdgcn_exp2f(x * -1.44269504089f)); }
; __device__ __forceinline__ float siluf_(float x) { return x * __builtin_amdgcn_rcpf(1.0f + __builtin_amdgcn_exp2f(x * -1.44269504089f)); }
;     __device__ __forceinline__ void epi_proj(const f32x4 (&acc)[2][2][4][2], const pg8::Unit& u, int wr, int wc, int fr, int fq) const {
;     ...
;                         const int slot = u.pn >> 2;
;                         bf16_t* rowp = act + (size_t)slot * SLOT_EL + (size_t)r * 1024 + (colt & 1023);
; #pragma unroll
;                         for (int bj = 0; bj < 2; ++bj) {
;                             f32x4 v0 = acc[ai][bj][m][0] * rstd, v1 = acc[ai][bj][m][1] * rstd;
;                             if (slot < 2) {
;                                 f32x2 a = gelu_pk((f32x2){v0[0], v0[1]}), b = gelu_pk((f32x2){v0[2], v0[3]}), c = gelu_pk((f32x2){v1[0], v1[1]}), d = gelu_pk((f32x2){v1[2], v1[3]});
;                                 v0 = (f32x4){a.x, a.y, b.x, b.y}; v1 = (f32x4){c.x, c.y, d.x, d.y};
;                             } else if (slot == 5) {
; #pragma unroll
;                                 for (int j = 0; j < 4; ++j) { v0[j] = siluf_(v0[j]); v1[j] = siluf_(v1[j]); }
;                             } else if (slot >= 6) {
; #pragma unroll
;                                 for (int j = 0; j < 4; ++j) { v0[j] = sigmoidf_(v0[j]); v1[j] = sigmoidf_(v1[j]); }
;                             }
;                             u32x4 w; w.x = cvt_pk_bf16(v0[0], v0[1]); w.y = cvt_pk_bf16(v0[2], v0[3]); w.z = cvt_pk_bf16(v1[0], v1[1]); w.w = cvt_pk_bf16(v1[2], v1[3]);
;                             *(u32x4*)(rowp + bj * 128) = w;
	v_rcp_f32_e32 v169, v169
	s_nop 0
	v_pk_mul_f32 v[146:147], v[146:147], v[168:169]
	s_nop 0
	v_add_f32_e32 v170, 1.0, v170
	v_add_f32_e32 v171, 1.0, v171
	v_rcp_f32_e32 v170, v170
	v_rcp_f32_e32 v171, v171
	s_nop 0
	v_pk_mul_f32 v[154:155], v[154:155], v[170:171]
	s_nop 0
	v_add_f32_e32 v172, 1.0, v172
	v_add_f32_e32 v173, 1.0, v173
	v_rcp_f32_e32 v172, v172
	v_rcp_f32_e32 v173, v173
	s_nop 0
	v_pk_mul_f32 v[142:143], v[142:143], v[172:173]
	s_nop 0
	v_add_f32_e32 v174, 1.0, v174
	v_add_f32_e32 v175, 1.0, v175
	v_rcp_f32_e32 v174, v174
	v_rcp_f32_e32 v175, v175
	s_nop 0
	v_pk_mul_f32 v[156:157], v[148:149], v[174:175]
	v_cvt_pk_bf16_f32 v146, v146, v147
	v_cvt_pk_bf16_f32 v147, v142, v143
	v_cvt_pk_bf16_f32 v148, v154, v155
	v_cvt_pk_bf16_f32 v149, v156, v157
	global_store_dwordx4 v[150:151], v[146:149], off
	v_pk_mul_f32 v[142:143], v[94:95], v[144:145] op_sel_hi:[1,0]
	s_mov_b64 s[0:1], 0x40000
	v_pk_mul_f32 v[146:147], v[92:93], v[144:145] op_sel_hi:[1,0]
	v_pk_mul_f32 v[148:149], v[90:91], v[144:145] op_sel_hi:[1,0]
	v_pk_mul_f32 v[144:145], v[88:89], v[144:145] op_sel_hi:[1,0]
	v_mul_f32_e32 v176, 0xbfb8aa3b, v146
	v_exp_f32_e32 v176, v176
	v_mul_f32_e32 v178, 0xbfb8aa3b, v144
	v_exp_f32_e32 v178, v178
	v_mul_f32_e32 v177, 0xbfb8aa3b, v147
	v_exp_f32_e32 v177, v177
	v_mul_f32_e32 v179, 0xbfb8aa3b, v145
	v_exp_f32_e32 v179, v179
	v_mul_f32_e32 v180, 0xbfb8aa3b, v142
	v_exp_f32_e32 v180, v180
	v_mul_f32_e32 v182, 0xbfb8aa3b, v148
	v_exp_f32_e32 v182, v182
	v_mul_f32_e32 v181, 0xbfb8aa3b, v143
	v_exp_f32_e32 v181, v181
	v_mul_f32_e32 v183, 0xbfb8aa3b, v149
	v_exp_f32_e32 v183, v183
	s_nop 0
	v_add_f32_e32 v176, 1.0, v176
	v_add_f32_e32 v177, 1.0, v177
	v_rcp_f32_e32 v176, v176
	v_rcp_f32_e32 v177, v177
	s_nop 0
	v_pk_mul_f32 v[146:147], v[146:147], v[176:177]
	s_nop 0
	v_add_f32_e32 v178, 1.0, v178
	v_add_f32_e32 v179, 1.0, v179
	v_rcp_f32_e32 v178, v178
	v_rcp_f32_e32 v179, v179
	s_nop 0
	v_pk_mul_f32 v[144:145], v[144:145], v[178:179]
	s_nop 0
	v_add_f32_e32 v180, 1.0, v180
	v_add_f32_e32 v181, 1.0, v181
	v_rcp_f32_e32 v180, v180
	v_rcp_f32_e32 v181, v181
	s_nop 0
	v_pk_mul_f32 v[154:155], v[142:143], v[180:181]
	s_nop 0
	v_add_f32_e32 v182, 1.0, v182
	v_add_f32_e32 v183, 1.0, v183
	v_rcp_f32_e32 v182, v182
	v_rcp_f32_e32 v183, v183
	s_nop 0
	v_pk_mul_f32 v[148:149], v[148:149], v[182:183]
	v_cvt_pk_bf16_f32 v142, v146, v147
	v_cvt_pk_bf16_f32 v143, v154, v155
	v_cvt_pk_bf16_f32 v144, v144, v145
	v_cvt_pk_bf16_f32 v145, v148, v149
	global_store_dwordx4 v[150:151], v[142:145], off offset:256
	v_pk_mul_f32 v[146:147], v[66:67], v[138:139] op_sel_hi:[1,0]
	v_pk_mul_f32 v[148:149], v[64:65], v[138:139] op_sel_hi:[1,0]
	v_lshl_add_u64 v[144:145], v[152:153], 0, v[140:141]
	v_pk_mul_f32 v[140:141], v[70:71], v[138:139] op_sel_hi:[1,0]
	v_pk_mul_f32 v[142:143], v[68:69], v[138:139] op_sel_hi:[1,0]
	v_mul_f32_e32 v184, 0xbfb8aa3b, v148
	v_exp_f32_e32 v184, v184
	v_mul_f32_e32 v186, 0xbfb8aa3b, v142
	v_exp_f32_e32 v186, v186
	v_mul_f32_e32 v187, 0xbfb8aa3b, v143
	v_exp_f32_e32 v187, v187
	v_mul_f32_e32 v185, 0xbfb8aa3b, v149
	v_exp_f32_e32 v185, v185
	v_mul_f32_e32 v188, 0xbfb8aa3b, v140
	v_exp_f32_e32 v188, v188
	v_mul_f32_e32 v190, 0xbfb8aa3b, v146
	v_exp_f32_e32 v190, v190
	v_mul_f32_e32 v189, 0xbfb8aa3b, v141
	v_exp_f32_e32 v189, v189
	v_mul_f32_e32 v191, 0xbfb8aa3b, v147
	v_exp_f32_e32 v191, v191
	s_nop 0
	v_add_f32_e32 v186, 1.0, v186
	v_add_f32_e32 v187, 1.0, v187
	v_rcp_f32_e32 v186, v186
	v_rcp_f32_e32 v187, v187
	s_nop 0
	v_pk_mul_f32 v[142:143], v[142:143], v[186:187]
	s_nop 0
	v_add_f32_e32 v184, 1.0, v184
	v_add_f32_e32 v185, 1.0, v185
	v_rcp_f32_e32 v184, v184
	v_rcp_f32_e32 v185, v185
	s_nop 0
	v_pk_mul_f32 v[148:149], v[148:149], v[184:185]
	s_nop 0
	v_add_f32_e32 v188, 1.0, v188
	v_add_f32_e32 v189, 1.0, v189
	v_rcp_f32_e32 v188, v188
	v_rcp_f32_e32 v189, v189
	s_nop 0
	v_pk_mul_f32 v[150:151], v[140:141], v[188:189]
	s_nop 0
	v_add_f32_e32 v190, 1.0, v190
	v_add_f32_e32 v191, 1.0, v191
	v_rcp_f32_e32 v190, v190
	v_rcp_f32_e32 v191, v191
	s_nop 0
	v_pk_mul_f32 v[146:147], v[146:147], v[190:191]
	v_cvt_pk_bf16_f32 v140, v142, v143
	v_cvt_pk_bf16_f32 v141, v150, v151
	v_cvt_pk_bf16_f32 v142, v148, v149
	v_cvt_pk_bf16_f32 v143, v146, v147
	global_store_dwordx4 v[144:145], v[140:143], off
	v_pk_mul_f32 v[146:147], v[74:75], v[138:139] op_sel_hi:[1,0]
	v_mul_f32_e32 v129, 0x45800000, v128
	v_pk_mul_f32 v[140:141], v[78:79], v[138:139] op_sel_hi:[1,0]
	v_pk_mul_f32 v[142:143], v[76:77], v[138:139] op_sel_hi:[1,0]
	v_pk_mul_f32 v[138:139], v[72:73], v[138:139] op_sel_hi:[1,0]
	v_mul_f32_e32 v164, 0xbfb8aa3b, v142
	v_exp_f32_e32 v164, v164
	v_mul_f32_e32 v166, 0xbfb8aa3b, v138
	v_exp_f32_e32 v166, v166
	v_mul_f32_e32 v167, 0xbfb8aa3b, v139
	v_exp_f32_e32 v167, v167
	v_mul_f32_e32 v165, 0xbfb8aa3b, v143
	v_exp_f32_e32 v165, v165
	s_nop 0
	v_add_f32_e32 v166, 1.0, v166
	v_add_f32_e32 v167, 1.0, v167
	v_rcp_f32_e32 v166, v166
	v_rcp_f32_e32 v167, v167
	s_nop 0
	v_pk_mul_f32 v[148:149], v[138:139], v[166:167]
	v_mul_f32_e32 v168, 0xbfb8aa3b, v140
	v_exp_f32_e32 v168, v168
	v_mov_b32_e32 v138, v140
	v_mul_f32_e32 v170, 0xbfb8aa3b, v146
	v_exp_f32_e32 v170, v170
	v_mov_b32_e32 v140, v146
	v_mul_f32_e32 v169, 0xbfb8aa3b, v141
	v_exp_f32_e32 v169, v169
	v_mov_b32_e32 v139, v141
	v_mul_f32_e32 v171, 0xbfb8aa3b, v147
	v_exp_f32_e32 v171, v171
	v_mov_b32_e32 v141, v147
	s_nop 0
	v_add_f32_e32 v164, 1.0, v164
	v_add_f32_e32 v165, 1.0, v165
	v_rcp_f32_e32 v164, v164
	v_rcp_f32_e32 v165, v165
	s_nop 0
	v_pk_mul_f32 v[142:143], v[142:143], v[164:165]
	s_nop 0
	v_add_f32_e32 v168, 1.0, v168
	v_add_f32_e32 v169, 1.0, v169
	v_rcp_f32_e32 v168, v168
; __device__ __forceinline__ unsigned cvt_pk_bf16(float lo, float hi) { const f32x2 v = {lo, hi}; const bf16v2_t b = __builtin_convertvector(v, bf16v2_t); return __builtin_bit_cast(unsigned, b); }
; __device__ __forceinline__ float sigmoidf_(float x) { return __builtin_amdgcn_rcpf(1.0f + __builtin_amdgcn_exp2f(x * -1.44269504089f)); }
; __device__ __forceinline__ float siluf_(float x) { return x * __builtin_amdgcn_rcpf(1.0f + __builtin_amdgcn_exp2f(x * -1.44269504089f)); }
;     __device__ __forceinline__ void epi_proj(const f32x4 (&acc)[2][2][4][2], const pg8::Unit& u, int wr, int wc, int fr, int fq) const {
;     ...
;                         const int slot = u.pn >> 2;
;                         bf16_t* rowp = act + (size_t)slot * SLOT_EL + (size_t)r * 1024 + (colt & 1023);
; #pragma unroll
;                         for (int bj = 0; bj < 2; ++bj) {
;                             f32x4 v0 = acc[ai][bj][m][0] * rstd, v1 = acc[ai][bj][m][1] * rstd;
;                             if (slot < 2) {
;                                 f32x2 a = gelu_pk((f32x2){v0[0], v0[1]}), b = gelu_pk((f32x2){v0[2], v0[3]}), c = gelu_pk((f32x2){v1[0], v1[1]}), d = gelu_pk((f32x2){v1[2], v1[3]});
;                                 v0 = (f32x4){a.x, a.y, b.x, b.y}; v1 = (f32x4){c.x, c.y, d.x, d.y};
;                             } else if (slot == 5) {
; #pragma unroll
;                                 for (int j = 0; j < 4; ++j) { v0[j] = siluf_(v0[j]); v1[j] = siluf_(v1[j]); }
;                             } else if (slot >= 6) {
; #pragma unroll
;                                 for (int j = 0; j < 4; ++j) { v0[j] = sigmoidf_(v0[j]); v1[j] = sigmoidf_(v1[j]); }
;                             }
;                             u32x4 w; w.x = cvt_pk_bf16(v0[0], v0[1]); w.y = cvt_pk_bf16(v0[2], v0[3]); w.z = cvt_pk_bf16(v1[0], v1[1]); w.w = cvt_pk_bf16(v1[2], v1[3]);
;                             *(u32x4*)(rowp + bj * 128) = w;
	v_rcp_f32_e32 v169, v169
	s_nop 0
	v_pk_mul_f32 v[150:151], v[138:139], v[168:169]
	s_nop 0
	v_add_f32_e32 v170, 1.0, v170
	v_add_f32_e32 v171, 1.0, v171
	v_rcp_f32_e32 v170, v170
	v_rcp_f32_e32 v171, v171
	s_nop 0
	v_pk_mul_f32 v[146:147], v[140:141], v[170:171]
	v_cvt_pk_bf16_f32 v138, v142, v143
	v_cvt_pk_bf16_f32 v139, v150, v151
	v_cvt_pk_bf16_f32 v140, v148, v149
	v_cvt_pk_bf16_f32 v141, v146, v147
	global_store_dwordx4 v[144:145], v[138:141], off offset:256
	v_pk_mul_f32 v[144:145], v[50:51], v[134:135] op_sel_hi:[1,0]
	v_pk_mul_f32 v[146:147], v[48:49], v[134:135] op_sel_hi:[1,0]
	v_pk_mul_f32 v[140:141], v[52:53], v[134:135] op_sel_hi:[1,0]
	v_pk_mul_f32 v[138:139], v[54:55], v[134:135] op_sel_hi:[1,0]
	v_mul_f32_e32 v172, 0xbfb8aa3b, v140
	v_exp_f32_e32 v172, v172
	v_mul_f32_e32 v173, 0xbfb8aa3b, v141
	v_exp_f32_e32 v173, v173
	v_mul_f32_e32 v174, 0xbfb8aa3b, v144
	v_exp_f32_e32 v174, v174
	v_mul_f32_e32 v175, 0xbfb8aa3b, v145
	v_exp_f32_e32 v175, v175
	v_lshl_add_u64 v[142:143], v[136:137], 0, s[0:1]
	v_mul_f32_e32 v176, 0xbfb8aa3b, v146
	v_exp_f32_e32 v176, v176
	s_nop 0
	v_add_f32_e32 v172, 1.0, v172
	v_add_f32_e32 v173, 1.0, v173
	v_rcp_f32_e32 v172, v172
	v_rcp_f32_e32 v173, v173
	s_nop 0
	v_pk_mul_f32 v[140:141], v[140:141], v[172:173]
	v_mul_f32_e32 v177, 0xbfb8aa3b, v147
	v_exp_f32_e32 v177, v177
	v_mul_f32_e32 v178, 0xbfb8aa3b, v138
	v_exp_f32_e32 v178, v178
	v_mul_f32_e32 v179, 0xbfb8aa3b, v139
	v_exp_f32_e32 v179, v179
	s_nop 0
	v_add_f32_e32 v174, 1.0, v174
	v_add_f32_e32 v175, 1.0, v175
	v_rcp_f32_e32 v174, v174
	v_rcp_f32_e32 v175, v175
	s_nop 0
	v_pk_mul_f32 v[144:145], v[144:145], v[174:175]
	s_mov_b32 s0, 0x40000
	v_cndmask_b32_e32 v128, v128, v129, vcc
	s_nop 0
	v_add_f32_e32 v176, 1.0, v176
	v_add_f32_e32 v177, 1.0, v177
	v_rcp_f32_e32 v176, v176
	v_rcp_f32_e32 v177, v177
	s_nop 0
	v_pk_mul_f32 v[146:147], v[146:147], v[176:177]
	s_nop 0
	v_add_f32_e32 v178, 1.0, v178
	v_add_f32_e32 v179, 1.0, v179
	v_rcp_f32_e32 v178, v178
	v_rcp_f32_e32 v179, v179
	s_nop 0
	v_pk_mul_f32 v[148:149], v[138:139], v[178:179]
	v_cvt_pk_bf16_f32 v138, v140, v141
	v_cvt_pk_bf16_f32 v141, v144, v145
	v_add_co_u32_e32 v144, vcc, s0, v136
	v_cvt_pk_bf16_f32 v139, v148, v149
	v_cvt_pk_bf16_f32 v140, v146, v147
	v_addc_co_u32_e32 v145, vcc, 0, v137, vcc
	global_store_dwordx4 v[144:145], v[138:141], off
	v_pk_mul_f32 v[144:145], v[58:59], v[134:135] op_sel_hi:[1,0]
	s_mov_b64 s[0:1], 0x48000
	v_pk_mul_f32 v[138:139], v[62:63], v[134:135] op_sel_hi:[1,0]
	v_pk_mul_f32 v[140:141], v[60:61], v[134:135] op_sel_hi:[1,0]
	v_pk_mul_f32 v[134:135], v[56:57], v[134:135] op_sel_hi:[1,0]
	v_mul_f32_e32 v180, 0xbfb8aa3b, v140
	v_exp_f32_e32 v180, v180
	v_mul_f32_e32 v182, 0xbfb8aa3b, v134
	v_exp_f32_e32 v182, v182
	v_mul_f32_e32 v181, 0xbfb8aa3b, v141
	v_exp_f32_e32 v181, v181
	v_mul_f32_e32 v183, 0xbfb8aa3b, v135
	v_exp_f32_e32 v183, v183
	v_mul_f32_e32 v186, 0xbfb8aa3b, v138
	v_exp_f32_e32 v186, v186
	v_mul_f32_e32 v184, 0xbfb8aa3b, v144
	v_exp_f32_e32 v184, v184
	v_mul_f32_e32 v187, 0xbfb8aa3b, v139
	v_exp_f32_e32 v187, v187
	v_mul_f32_e32 v185, 0xbfb8aa3b, v145
	v_exp_f32_e32 v185, v185
	s_nop 0
	v_add_f32_e32 v180, 1.0, v180
	v_add_f32_e32 v181, 1.0, v181
	v_rcp_f32_e32 v180, v180
	v_rcp_f32_e32 v181, v181
	s_nop 0
	v_pk_mul_f32 v[140:141], v[140:141], v[180:181]
	s_nop 0
	v_add_f32_e32 v182, 1.0, v182
	v_add_f32_e32 v183, 1.0, v183
	v_rcp_f32_e32 v182, v182
	v_rcp_f32_e32 v183, v183
	s_nop 0
	v_pk_mul_f32 v[134:135], v[134:135], v[182:183]
	s_nop 0
	v_add_f32_e32 v186, 1.0, v186
	v_add_f32_e32 v187, 1.0, v187
	v_rcp_f32_e32 v186, v186
	v_rcp_f32_e32 v187, v187
	s_nop 0
	v_pk_mul_f32 v[146:147], v[138:139], v[186:187]
	s_nop 0
	v_add_f32_e32 v184, 1.0, v184
	v_add_f32_e32 v185, 1.0, v185
	v_rcp_f32_e32 v184, v184
	v_rcp_f32_e32 v185, v185
	s_nop 0
	v_pk_mul_f32 v[144:145], v[144:145], v[184:185]
	v_cvt_pk_bf16_f32 v138, v140, v141
	v_cvt_pk_bf16_f32 v139, v146, v147
	v_cvt_pk_bf16_f32 v140, v134, v135
	v_cvt_pk_bf16_f32 v141, v144, v145
	global_store_dwordx4 v[142:143], v[138:141], off offset:256
	v_pk_mul_f32 v[134:135], v[38:39], v[132:133] op_sel_hi:[1,0]
	v_pk_mul_f32 v[144:145], v[32:33], v[132:133] op_sel_hi:[1,0]
	v_pk_mul_f32 v[138:139], v[36:37], v[132:133] op_sel_hi:[1,0]
	v_pk_mul_f32 v[140:141], v[34:35], v[132:133] op_sel_hi:[1,0]
	v_mul_f32_e32 v188, 0xbfb8aa3b, v138
	v_exp_f32_e32 v188, v188
	v_mul_f32_e32 v189, 0xbfb8aa3b, v139
	v_exp_f32_e32 v189, v189
	v_mul_f32_e32 v190, 0xbfb8aa3b, v134
	v_exp_f32_e32 v190, v190
	v_mul_f32_e32 v191, 0xbfb8aa3b, v135
	v_exp_f32_e32 v191, v191
	v_lshl_add_u64 v[142:143], v[136:137], 0, s[0:1]
	v_mul_f32_e32 v166, 0xbfb8aa3b, v144
	v_exp_f32_e32 v166, v166
	s_nop 0
	v_add_f32_e32 v188, 1.0, v188
	v_add_f32_e32 v189, 1.0, v189
	v_rcp_f32_e32 v188, v188
	v_rcp_f32_e32 v189, v189
	s_nop 0
	v_pk_mul_f32 v[138:139], v[138:139], v[188:189]
	v_mul_f32_e32 v167, 0xbfb8aa3b, v145
	v_exp_f32_e32 v167, v167
	v_mul_f32_e32 v164, 0xbfb8aa3b, v140
	v_exp_f32_e32 v164, v164
	s_nop 0
	v_add_f32_e32 v190, 1.0, v190
	v_add_f32_e32 v191, 1.0, v191
	v_rcp_f32_e32 v190, v190
	v_rcp_f32_e32 v191, v191
	s_nop 0
	v_pk_mul_f32 v[134:135], v[134:135], v[190:191]
	v_mul_f32_e32 v165, 0xbfb8aa3b, v141
	v_exp_f32_e32 v165, v165
	s_mov_b32 s0, 0x48000
	s_nop 0
	v_add_f32_e32 v166, 1.0, v166
	v_add_f32_e32 v167, 1.0, v167
	v_rcp_f32_e32 v166, v166
	v_rcp_f32_e32 v167, v167
	s_nop 0
	v_pk_mul_f32 v[144:145], v[144:145], v[166:167]
	s_nop 0
	v_add_f32_e32 v164, 1.0, v164
	v_add_f32_e32 v165, 1.0, v165
	v_rcp_f32_e32 v164, v164
	v_rcp_f32_e32 v165, v165
	s_nop 0
	v_pk_mul_f32 v[146:147], v[140:141], v[164:165]
; __device__ __forceinline__ unsigned cvt_pk_bf16(float lo, float hi) { const f32x2 v = {lo, hi}; const bf16v2_t b = __builtin_convertvector(v, bf16v2_t); return __builtin_bit_cast(unsigned, b); }
; __device__ __forceinline__ float sigmoidf_(float x) { return __builtin_amdgcn_rcpf(1.0f + __builtin_amdgcn_exp2f(x * -1.44269504089f)); }
; __device__ __forceinline__ float siluf_(float x) { return x * __builtin_amdgcn_rcpf(1.0f + __builtin_amdgcn_exp2f(x * -1.44269504089f)); }
;     __device__ __forceinline__ void epi_proj(const f32x4 (&acc)[2][2][4][2], const pg8::Unit& u, int wr, int wc, int fr, int fq) const {
;     ...
;                         const int slot = u.pn >> 2;
;                         bf16_t* rowp = act + (size_t)slot * SLOT_EL + (size_t)r * 1024 + (colt & 1023);
; #pragma unroll
;                         for (int bj = 0; bj < 2; ++bj) {
;                             f32x4 v0 = acc[ai][bj][m][0] * rstd, v1 = acc[ai][bj][m][1] * rstd;
;                             if (slot < 2) {
;                                 f32x2 a = gelu_pk((f32x2){v0[0], v0[1]}), b = gelu_pk((f32x2){v0[2], v0[3]}), c = gelu_pk((f32x2){v1[0], v1[1]}), d = gelu_pk((f32x2){v1[2], v1[3]});
;                                 v0 = (f32x4){a.x, a.y, b.x, b.y}; v1 = (f32x4){c.x, c.y, d.x, d.y};
;                             } else if (slot == 5) {
; #pragma unroll
;                                 for (int j = 0; j < 4; ++j) { v0[j] = siluf_(v0[j]); v1[j] = siluf_(v1[j]); }
;                             } else if (slot >= 6) {
; #pragma unroll
;                                 for (int j = 0; j < 4; ++j) { v0[j] = sigmoidf_(v0[j]); v1[j] = sigmoidf_(v1[j]); }
;                             }
;                             u32x4 w; w.x = cvt_pk_bf16(v0[0], v0[1]); w.y = cvt_pk_bf16(v0[2], v0[3]); w.z = cvt_pk_bf16(v1[0], v1[1]); w.w = cvt_pk_bf16(v1[2], v1[3]);
;                             *(u32x4*)(rowp + bj * 128) = w;
	v_cvt_pk_bf16_f32 v138, v138, v139
	v_cvt_pk_bf16_f32 v139, v134, v135
	v_add_co_u32_e32 v134, vcc, s0, v136
	v_cvt_pk_bf16_f32 v140, v144, v145
	v_cvt_pk_bf16_f32 v141, v146, v147
	v_addc_co_u32_e32 v135, vcc, 0, v137, vcc
	global_store_dwordx4 v[134:135], v[138:141], off
	v_pk_mul_f32 v[134:135], v[46:47], v[132:133] op_sel_hi:[1,0]
	s_mov_b64 s[0:1], 0x50000
	v_pk_mul_f32 v[138:139], v[44:45], v[132:133] op_sel_hi:[1,0]
	v_pk_mul_f32 v[140:141], v[42:43], v[132:133] op_sel_hi:[1,0]
	v_pk_mul_f32 v[132:133], v[40:41], v[132:133] op_sel_hi:[1,0]
	v_mul_f32_e32 v168, 0xbfb8aa3b, v138
	v_exp_f32_e32 v168, v168
	v_mul_f32_e32 v170, 0xbfb8aa3b, v132
	v_exp_f32_e32 v170, v170
	v_mul_f32_e32 v171, 0xbfb8aa3b, v133
	v_exp_f32_e32 v171, v171
	v_mul_f32_e32 v169, 0xbfb8aa3b, v139
	v_exp_f32_e32 v169, v169
	s_nop 0
	v_add_f32_e32 v170, 1.0, v170
	v_add_f32_e32 v171, 1.0, v171
	v_rcp_f32_e32 v170, v170
	v_rcp_f32_e32 v171, v171
	s_nop 0
	v_pk_mul_f32 v[144:145], v[132:133], v[170:171]
	v_mul_f32_e32 v172, 0xbfb8aa3b, v134
	v_exp_f32_e32 v172, v172
	v_mov_b32_e32 v132, v134
	v_mul_f32_e32 v174, 0xbfb8aa3b, v140
	v_exp_f32_e32 v174, v174
	v_mov_b32_e32 v134, v140
	v_mul_f32_e32 v173, 0xbfb8aa3b, v135
	v_exp_f32_e32 v173, v173
	v_mov_b32_e32 v133, v135
	v_mul_f32_e32 v175, 0xbfb8aa3b, v141
	v_exp_f32_e32 v175, v175
	v_mov_b32_e32 v135, v141
	s_nop 0
	v_add_f32_e32 v168, 1.0, v168
	v_add_f32_e32 v169, 1.0, v169
	v_rcp_f32_e32 v168, v168
	v_rcp_f32_e32 v169, v169
	s_nop 0
	v_pk_mul_f32 v[138:139], v[138:139], v[168:169]
	s_nop 0
	v_add_f32_e32 v172, 1.0, v172
	v_add_f32_e32 v173, 1.0, v173
	v_rcp_f32_e32 v172, v172
	v_rcp_f32_e32 v173, v173
	s_nop 0
	v_pk_mul_f32 v[146:147], v[132:133], v[172:173]
	s_nop 0
	v_add_f32_e32 v174, 1.0, v174
	v_add_f32_e32 v175, 1.0, v175
	v_rcp_f32_e32 v174, v174
	v_rcp_f32_e32 v175, v175
	s_nop 0
	v_pk_mul_f32 v[140:141], v[134:135], v[174:175]
	v_cvt_pk_bf16_f32 v132, v138, v139
	v_cvt_pk_bf16_f32 v133, v146, v147
	v_cvt_pk_bf16_f32 v134, v144, v145
	v_cvt_pk_bf16_f32 v135, v140, v141
	global_store_dwordx4 v[142:143], v[132:135], off offset:256
	v_pk_mul_f32 v[140:141], v[18:19], v[130:131] op_sel_hi:[1,0]
	v_pk_mul_f32 v[142:143], v[16:17], v[130:131] op_sel_hi:[1,0]
	v_pk_mul_f32 v[134:135], v[20:21], v[130:131] op_sel_hi:[1,0]
	v_pk_mul_f32 v[132:133], v[22:23], v[130:131] op_sel_hi:[1,0]
	v_mul_f32_e32 v176, 0xbfb8aa3b, v134
	v_exp_f32_e32 v176, v176
	v_mul_f32_e32 v177, 0xbfb8aa3b, v135
	v_exp_f32_e32 v177, v177
	v_mul_f32_e32 v178, 0xbfb8aa3b, v140
	v_exp_f32_e32 v178, v178
	v_mul_f32_e32 v179, 0xbfb8aa3b, v141
	v_exp_f32_e32 v179, v179
	v_lshl_add_u64 v[138:139], v[136:137], 0, s[0:1]
	v_mul_f32_e32 v180, 0xbfb8aa3b, v142
	v_exp_f32_e32 v180, v180
	s_nop 0
	v_add_f32_e32 v176, 1.0, v176
	v_add_f32_e32 v177, 1.0, v177
	v_rcp_f32_e32 v176, v176
	v_rcp_f32_e32 v177, v177
	s_nop 0
	v_pk_mul_f32 v[134:135], v[134:135], v[176:177]
	v_mul_f32_e32 v181, 0xbfb8aa3b, v143
	v_exp_f32_e32 v181, v181
	v_mul_f32_e32 v182, 0xbfb8aa3b, v132
	v_exp_f32_e32 v182, v182
	v_mul_f32_e32 v183, 0xbfb8aa3b, v133
	v_exp_f32_e32 v183, v183
	s_nop 0
	v_add_f32_e32 v178, 1.0, v178
	v_add_f32_e32 v179, 1.0, v179
	v_rcp_f32_e32 v178, v178
	v_rcp_f32_e32 v179, v179
	s_nop 0
	v_pk_mul_f32 v[140:141], v[140:141], v[178:179]
	s_mov_b32 s0, 0x50000
	s_nop 0
	v_add_f32_e32 v180, 1.0, v180
	v_add_f32_e32 v181, 1.0, v181
	v_rcp_f32_e32 v180, v180
	v_rcp_f32_e32 v181, v181
	s_nop 0
	v_pk_mul_f32 v[142:143], v[142:143], v[180:181]
	s_nop 0
	v_add_f32_e32 v182, 1.0, v182
	v_add_f32_e32 v183, 1.0, v183
	v_rcp_f32_e32 v182, v182
	v_rcp_f32_e32 v183, v183
	s_nop 0
	v_pk_mul_f32 v[144:145], v[132:133], v[182:183]
	v_cvt_pk_bf16_f32 v132, v134, v135
	v_cvt_pk_bf16_f32 v135, v140, v141
	v_add_co_u32_e32 v140, vcc, s0, v136
	v_cvt_pk_bf16_f32 v133, v144, v145
	v_cvt_pk_bf16_f32 v134, v142, v143
	v_addc_co_u32_e32 v141, vcc, 0, v137, vcc
	global_store_dwordx4 v[140:141], v[132:135], off
	v_pk_mul_f32 v[140:141], v[26:27], v[130:131] op_sel_hi:[1,0]
	s_mov_b64 s[0:1], 0x58000
	v_pk_mul_f32 v[132:133], v[30:31], v[130:131] op_sel_hi:[1,0]
	v_pk_mul_f32 v[134:135], v[28:29], v[130:131] op_sel_hi:[1,0]
	v_pk_mul_f32 v[130:131], v[24:25], v[130:131] op_sel_hi:[1,0]
	v_mul_f32_e32 v186, 0xbfb8aa3b, v134
	v_exp_f32_e32 v186, v186
	v_mul_f32_e32 v184, 0xbfb8aa3b, v130
	v_exp_f32_e32 v184, v184
	v_mul_f32_e32 v185, 0xbfb8aa3b, v131
	v_exp_f32_e32 v185, v185
	v_mul_f32_e32 v187, 0xbfb8aa3b, v135
	v_exp_f32_e32 v187, v187
	s_nop 0
	v_add_f32_e32 v184, 1.0, v184
	v_add_f32_e32 v185, 1.0, v185
	v_rcp_f32_e32 v184, v184
	v_rcp_f32_e32 v185, v185
	s_nop 0
	v_pk_mul_f32 v[142:143], v[130:131], v[184:185]
	v_mul_f32_e32 v188, 0xbfb8aa3b, v132
	v_exp_f32_e32 v188, v188
	v_mov_b32_e32 v130, v132
	v_mul_f32_e32 v190, 0xbfb8aa3b, v140
	v_exp_f32_e32 v190, v190
; __device__ __forceinline__ unsigned cvt_pk_bf16(float lo, float hi) { const f32x2 v = {lo, hi}; const bf16v2_t b = __builtin_convertvector(v, bf16v2_t); return __builtin_bit_cast(unsigned, b); }
; __device__ __forceinline__ float sigmoidf_(float x) { return __builtin_amdgcn_rcpf(1.0f + __builtin_amdgcn_exp2f(x * -1.44269504089f)); }
; __device__ __forceinline__ float siluf_(float x) { return x * __builtin_amdgcn_rcpf(1.0f + __builtin_amdgcn_exp2f(x * -1.44269504089f)); }
;     __device__ __forceinline__ void epi_proj(const f32x4 (&acc)[2][2][4][2], const pg8::Unit& u, int wr, int wc, int fr, int fq) const {
;     ...
;                     if (u.pn == 32) {
;     ...
;                         const int slot = u.pn >> 2;
;                         bf16_t* rowp = act + (size_t)slot * SLOT_EL + (size_t)r * 1024 + (colt & 1023);
; #pragma unroll
;                         for (int bj = 0; bj < 2; ++bj) {
;                             f32x4 v0 = acc[ai][bj][m][0] * rstd, v1 = acc[ai][bj][m][1] * rstd;
;                             if (slot < 2) {
;                                 f32x2 a = gelu_pk((f32x2){v0[0], v0[1]}), b = gelu_pk((f32x2){v0[2], v0[3]}), c = gelu_pk((f32x2){v1[0], v1[1]}), d = gelu_pk((f32x2){v1[2], v1[3]});
;                                 v0 = (f32x4){a.x, a.y, b.x, b.y}; v1 = (f32x4){c.x, c.y, d.x, d.y};
;                             } else if (slot == 5) {
; #pragma unroll
;                                 for (int j = 0; j < 4; ++j) { v0[j] = siluf_(v0[j]); v1[j] = siluf_(v1[j]); }
;                             } else if (slot >= 6) {
; #pragma unroll
;                                 for (int j = 0; j < 4; ++j) { v0[j] = sigmoidf_(v0[j]); v1[j] = sigmoidf_(v1[j]); }
;                             }
;                             u32x4 w; w.x = cvt_pk_bf16(v0[0], v0[1]); w.y = cvt_pk_bf16(v0[2], v0[3]); w.z = cvt_pk_bf16(v1[0], v1[1]); w.w = cvt_pk_bf16(v1[2], v1[3]);
;                             *(u32x4*)(rowp + bj * 128) = w;
	v_mov_b32_e32 v132, v140
	v_mul_f32_e32 v189, 0xbfb8aa3b, v133
	v_exp_f32_e32 v189, v189
	v_mov_b32_e32 v131, v133
	v_mul_f32_e32 v191, 0xbfb8aa3b, v141
	v_exp_f32_e32 v191, v191
	v_mov_b32_e32 v133, v141
	s_nop 0
	v_add_f32_e32 v186, 1.0, v186
	v_add_f32_e32 v187, 1.0, v187
	v_rcp_f32_e32 v186, v186
	v_rcp_f32_e32 v187, v187
	s_nop 0
	v_pk_mul_f32 v[134:135], v[134:135], v[186:187]
	s_nop 0
	v_add_f32_e32 v188, 1.0, v188
	v_add_f32_e32 v189, 1.0, v189
	v_rcp_f32_e32 v188, v188
	v_rcp_f32_e32 v189, v189
	s_nop 0
	v_pk_mul_f32 v[144:145], v[130:131], v[188:189]
	s_nop 0
	v_add_f32_e32 v190, 1.0, v190
	v_add_f32_e32 v191, 1.0, v191
	v_rcp_f32_e32 v190, v190
	v_rcp_f32_e32 v191, v191
	s_nop 0
	v_pk_mul_f32 v[140:141], v[132:133], v[190:191]
	v_cvt_pk_bf16_f32 v130, v134, v135
	v_cvt_pk_bf16_f32 v131, v144, v145
	v_cvt_pk_bf16_f32 v132, v142, v143
	v_cvt_pk_bf16_f32 v133, v140, v141
	global_store_dwordx4 v[138:139], v[130:133], off offset:256
	v_pk_mul_f32 v[138:139], v[2:3], v[128:129] op_sel_hi:[1,0]
	v_pk_mul_f32 v[140:141], v[0:1], v[128:129] op_sel_hi:[1,0]
	v_pk_mul_f32 v[130:131], v[6:7], v[128:129] op_sel_hi:[1,0]
	v_pk_mul_f32 v[132:133], v[4:5], v[128:129] op_sel_hi:[1,0]
	v_lshl_add_u64 v[134:135], v[136:137], 0, s[0:1]
	v_mul_f32_e32 v166, 0xbfb8aa3b, v132
	v_exp_f32_e32 v166, v166
	v_mul_f32_e32 v164, 0xbfb8aa3b, v140
	v_exp_f32_e32 v164, v164
	v_mul_f32_e32 v167, 0xbfb8aa3b, v133
	v_exp_f32_e32 v167, v167
	v_mul_f32_e32 v165, 0xbfb8aa3b, v141
	v_exp_f32_e32 v165, v165
	v_mul_f32_e32 v170, 0xbfb8aa3b, v130
	v_exp_f32_e32 v170, v170
	v_mul_f32_e32 v168, 0xbfb8aa3b, v138
	v_exp_f32_e32 v168, v168
	v_mul_f32_e32 v171, 0xbfb8aa3b, v131
	v_exp_f32_e32 v171, v171
	v_mul_f32_e32 v169, 0xbfb8aa3b, v139
	v_exp_f32_e32 v169, v169
	s_mov_b32 s0, 0x58000
	s_nop 0
	v_add_f32_e32 v166, 1.0, v166
	v_add_f32_e32 v167, 1.0, v167
	v_rcp_f32_e32 v166, v166
	v_rcp_f32_e32 v167, v167
	s_nop 0
	v_pk_mul_f32 v[132:133], v[132:133], v[166:167]
	s_nop 0
	v_add_f32_e32 v164, 1.0, v164
	v_add_f32_e32 v165, 1.0, v165
	v_rcp_f32_e32 v164, v164
	v_rcp_f32_e32 v165, v165
	s_nop 0
	v_pk_mul_f32 v[140:141], v[140:141], v[164:165]
	s_nop 0
	v_add_f32_e32 v170, 1.0, v170
	v_add_f32_e32 v171, 1.0, v171
	v_rcp_f32_e32 v170, v170
	v_rcp_f32_e32 v171, v171
	s_nop 0
	v_pk_mul_f32 v[142:143], v[130:131], v[170:171]
	s_nop 0
	v_add_f32_e32 v168, 1.0, v168
	v_add_f32_e32 v169, 1.0, v169
	v_rcp_f32_e32 v168, v168
	v_rcp_f32_e32 v169, v169
	s_nop 0
	v_pk_mul_f32 v[138:139], v[138:139], v[168:169]
	v_add_co_u32_e32 v136, vcc, s0, v136
	v_cvt_pk_bf16_f32 v130, v132, v133
	v_cvt_pk_bf16_f32 v131, v142, v143
	v_cvt_pk_bf16_f32 v132, v140, v141
	v_cvt_pk_bf16_f32 v133, v138, v139
	v_addc_co_u32_e32 v137, vcc, 0, v137, vcc
	global_store_dwordx4 v[136:137], v[130:133], off
	v_pk_mul_f32 v[136:137], v[10:11], v[128:129] op_sel_hi:[1,0]
	s_nop 0
	v_pk_mul_f32 v[130:131], v[14:15], v[128:129] op_sel_hi:[1,0]
	v_pk_mul_f32 v[132:133], v[12:13], v[128:129] op_sel_hi:[1,0]
	v_pk_mul_f32 v[128:129], v[8:9], v[128:129] op_sel_hi:[1,0]
	v_mul_f32_e32 v172, 0xbfb8aa3b, v132
	v_exp_f32_e32 v172, v172
	v_mul_f32_e32 v174, 0xbfb8aa3b, v128
	v_exp_f32_e32 v174, v174
	v_mul_f32_e32 v175, 0xbfb8aa3b, v129
	v_exp_f32_e32 v175, v175
	v_mul_f32_e32 v173, 0xbfb8aa3b, v133
	v_exp_f32_e32 v173, v173
	s_nop 0
	v_add_f32_e32 v174, 1.0, v174
	v_add_f32_e32 v175, 1.0, v175
	v_rcp_f32_e32 v174, v174
	v_rcp_f32_e32 v175, v175
	s_nop 0
	v_pk_mul_f32 v[138:139], v[128:129], v[174:175]
	v_mul_f32_e32 v176, 0xbfb8aa3b, v130
	v_exp_f32_e32 v176, v176
	v_mov_b32_e32 v128, v130
	v_mul_f32_e32 v178, 0xbfb8aa3b, v136
	v_exp_f32_e32 v178, v178
	v_mov_b32_e32 v130, v136
	v_mul_f32_e32 v177, 0xbfb8aa3b, v131
	v_exp_f32_e32 v177, v177
	v_mov_b32_e32 v129, v131
	v_mul_f32_e32 v179, 0xbfb8aa3b, v137
	v_exp_f32_e32 v179, v179
	v_mov_b32_e32 v131, v137
	s_nop 0
	v_add_f32_e32 v172, 1.0, v172
	v_add_f32_e32 v173, 1.0, v173
	v_rcp_f32_e32 v172, v172
	v_rcp_f32_e32 v173, v173
	s_nop 0
	v_pk_mul_f32 v[132:133], v[132:133], v[172:173]
	s_nop 0
	v_add_f32_e32 v176, 1.0, v176
	v_add_f32_e32 v177, 1.0, v177
	v_rcp_f32_e32 v176, v176
	v_rcp_f32_e32 v177, v177
	s_nop 0
	v_pk_mul_f32 v[140:141], v[128:129], v[176:177]
	s_nop 0
	v_add_f32_e32 v178, 1.0, v178
	v_add_f32_e32 v179, 1.0, v179
	v_rcp_f32_e32 v178, v178
	v_rcp_f32_e32 v179, v179
	s_nop 0
	v_pk_mul_f32 v[136:137], v[130:131], v[178:179]
	v_cvt_pk_bf16_f32 v128, v132, v133
	v_cvt_pk_bf16_f32 v129, v140, v141
	v_cvt_pk_bf16_f32 v130, v138, v139
	v_cvt_pk_bf16_f32 v131, v136, v137
	global_store_dwordx4 v[134:135], v[128:131], off offset:256
	s_branch .LBB0_701
.LBB0_1031:
	s_cmp_eq_u32 s88, 32
	s_cbranch_scc1 .Lproj_orig
	s_lshr_b32 s100, s88, 2
	s_cmp_ge_u32 s100, 6
	s_cbranch_scc1 .Lepi_sig
	s_cmp_eq_u32 s100, 5
	s_cbranch_scc1 .Lepi_silu

; __global__ void __launch_bounds__(NTHREADS, 2) fwd_megakernel(Params p) {
	.amdhsa_kernel _Z14fwd_megakernel6Params
		.amdhsa_group_segment_fixed_size 0
		.amdhsa_private_segment_fixed_size 0
		.amdhsa_kernarg_size 440
		.amdhsa_user_sgpr_count 2
		.amdhsa_user_sgpr_dispatch_ptr 0
		.amdhsa_user_sgpr_queue_ptr 0
		.amdhsa_user_sgpr_kernarg_segment_ptr 1
		.amdhsa_user_sgpr_dispatch_id 0
		.amdhsa_user_sgpr_kernarg_preload_length 0
		.amdhsa_user_sgpr_kernarg_preload_offset 0
		.amdhsa_user_sgpr_private_segment_size 0
		.amdhsa_uses_dynamic_stack 0
		.amdhsa_enable_private_segment 0
		.amdhsa_system_sgpr_workgroup_id_x 1
		.amdhsa_system_sgpr_workgroup_id_y 0
		.amdhsa_system_sgpr_workgroup_id_z 0
		.amdhsa_system_sgpr_workgroup_info 0
		.amdhsa_system_vgpr_workitem_id 2
		.amdhsa_next_free_vgpr 256
		.amdhsa_next_free_sgpr 102
		.amdhsa_accum_offset 256
		.amdhsa_reserve_vcc 1
		.amdhsa_float_round_mode_32 0
		.amdhsa_float_round_mode_16_64 0
		.amdhsa_float_denorm_mode_32 3
		.amdhsa_float_denorm_mode_16_64 3
		.amdhsa_dx10_clamp 1
		.amdhsa_ieee_mode 1
		.amdhsa_fp16_overflow 0
		.amdhsa_tg_split 0
		.amdhsa_exception_fp_ieee_invalid_op 0
		.amdhsa_exception_fp_denorm_src 0
		.amdhsa_exception_fp_ieee_div_zero 0
		.amdhsa_exception_fp_ieee_overflow 0
		.amdhsa_exception_fp_ieee_underflow 0
		.amdhsa_exception_fp_ieee_inexact 0
		.amdhsa_exception_int_div_zero 0
	.end_amdhsa_kernel

; __global__ void __launch_bounds__(NTHREADS, 2) fwd_megakernel(Params p) {
amdhsa.kernels:
  - .agpr_count:     0
    .args:
      - .offset:         0
        .size:           184
        .value_kind:     by_value
      - .offset:         184
        .size:           4
        .value_kind:     hidden_block_count_x
      - .offset:         188
        .size:           4
        .value_kind:     hidden_block_count_y
      - .offset:         192
        .size:           4
        .value_kind:     hidden_block_count_z
      - .offset:         196
        .size:           2
        .value_kind:     hidden_group_size_x
      - .offset:         198
        .size:           2
        .value_kind:     hidden_group_size_y
      - .offset:         200
        .size:           2
        .value_kind:     hidden_group_size_z
      - .offset:         202
        .size:           2
        .value_kind:     hidden_remainder_x
      - .offset:         204
        .size:           2
        .value_kind:     hidden_remainder_y
      - .offset:         206
        .size:           2
        .value_kind:     hidden_remainder_z
      - .offset:         224
        .size:           8
        .value_kind:     hidden_global_offset_x
      - .offset:         232
        .size:           8
        .value_kind:     hidden_global_offset_y
      - .offset:         240
        .size:           8
        .value_kind:     hidden_global_offset_z
      - .offset:         248
        .size:           2
        .value_kind:     hidden_grid_dims
      - .offset:         272
        .size:           8
        .value_kind:     hidden_multigrid_sync_arg
      - .offset:         304
        .size:           4
        .value_kind:     hidden_dynamic_lds_size
    .group_segment_fixed_size: 0
    .kernarg_segment_align: 8
    .kernarg_segment_size: 440
    .language:       OpenCL C
    .language_version:
      - 2
      - 0
    .max_flat_workgroup_size: 512
    .name:           _Z14fwd_megakernel6Params
    .private_segment_fixed_size: 0
    .sgpr_count:     108
    .sgpr_spill_count: 189
    .symbol:         _Z14fwd_megakernel6Params.kd
    .uniform_work_group_size: 1
    .uses_dynamic_stack: false
    .vgpr_count:     256
    .vgpr_spill_count: 0
    .wavefront_size: 64
